# v012 + E1(layer 0) panel order flipped + inv4 product in GELU/SwiGLU epilogues: 4 v_mov + v_pk_mul replaced by 2 v_mul (48 sites)
# baseline (speedup 1.0000x reference)
; template <int x_mode_in>
; __device__ __forceinline__ void phase_elem(const Params& p, bool prev, bool has_y, int l_res, int jg, int ngi_res, int x_mode_out, bool write_h, int l_h, int jsh, int ngi_h) {
;     ...
;     for (int b = gw; b < NTOK / 16; b += NGW) {
;         const int pos = prev ? 383 - (b >> 4) : (b >> 4), pmo = 48 * ((pos & 63) >> 3) + 8 * (pos >> 6) + (pos & 7);
;         const int tok0 = pmo * 256 + (b & 15) * 16, s = seq_of(tok0);
;         f32x4 ar[2][2], ah[2][2], sh[2][2];
; #pragma unroll
;         for (int j = 0; j < 2; ++j)
; #pragma unroll
;             for (int k = 0; k < 2; ++k) { ar[j][k] = (f32x4){0.f, 0.f, 0.f, 0.f}; ah[j][k] = ar[j][k]; sh[j][k] = ar[j][k]; }
;         if (has_y) { const float* gp = mod + (((size_t)s * 4 + l_res) * 6 + jg) * 1024 + 8 * lane; const float* np = norm_g + (l_res * 4 + ngi_res) * 1024 + 8 * lane;
; #pragma unroll
;             for (int j = 0; j < 2; ++j)
; #pragma unroll
;                 for (int k = 0; k < 2; ++k) ar[j][k] = *(const f32x4*)(gp + 512 * j + 4 * k) * *(const f32x4*)(np + 512 * j + 4 * k); }
;         if (write_h) { const float* shp = mod + (((size_t)s * 4 + l_h) * 6 + jsh) * 1024 + 8 * lane; const float* scp = shp + 1024; const float* np = norm_g + (l_h * 4 + ngi_h) * 1024 + 8 * lane;
; #pragma unroll
;             for (int j = 0; j < 2; ++j)
; #pragma unroll
;                 for (int k = 0; k < 2; ++k) { ah[j][k] = *(const f32x4*)(np + 512 * j + 4 * k) * (*(const f32x4*)(scp + 512 * j + 4 * k) + 1.0f); sh[j][k] = *(const f32x4*)(shp + 512 * j + 4 * k); } }
.LBB0_104:
	s_ashr_i32 s0, s4, 4
	s_sub_i32 s0, 0x17f, s0
	s_bfe_u32 s1, s0, 0x30003
	s_lshr_b32 s3, s0, 3
	s_mul_i32 s1, s1, 48
	s_and_b32 s3, s3, -8
	s_add_i32 s1, s1, s3
	s_and_b32 s0, s0, 7
	s_or_b32 s0, s1, s0
	s_lshl_b32 s3, s4, 4
	s_lshl_b32 s0, s0, 8
	s_and_b32 s3, s3, 0xf0
	s_and_b32 s2, s33, 0xf0
	s_or_b32 s38, s0, s3
	s_cmp_lt_i32 s38, 0x10000
	s_cselect_b64 s[10:11], -1, 0
	s_add_i32 s3, s0, 0xffff0000
	s_lshr_b32 s34, s3, 13
	s_add_i32 s39, s34, 32
	s_lshr_b32 s1, s1, 3
	s_and_b64 s[34:35], s[10:11], exec
	s_cselect_b32 s1, s1, s39
	s_mul_i32 s34, s1, 24
	s_ashr_i32 s35, s34, 31
	s_lshl_b64 s[34:35], s[34:35], 12
	v_lshl_add_u64 v[14:15], v[82:83], 0, s[34:35]
	s_mov_b64 s[34:35], 0x1000
	v_lshl_add_u64 v[2:3], v[14:15], 0, s[34:35]
	s_mov_b64 s[34:35], 0x1800
	v_lshl_add_u64 v[12:13], v[14:15], 0, s[34:35]
	s_add_i32 s1, s38, 0xffff0000
	s_ashr_i32 s34, s38, 31
	s_and_b64 s[10:11], s[10:11], exec
	v_readlane_b32 s40, v247, 33
	s_cselect_b32 s11, s34, 0
	s_cselect_b32 s10, s38, s1
	v_readlane_b32 s41, v247, 34
	v_readlane_b32 s42, v247, 35
	v_readlane_b32 s43, v247, 36
	s_cselect_b32 s1, s41, s43
	s_cselect_b32 s34, s40, s42
	s_lshl_b64 s[10:11], s[10:11], 12
	v_add_co_u32_e32 v10, vcc, s83, v14
	s_add_u32 s10, s34, s10
	s_nop 0
	v_addc_co_u32_e32 v11, vcc, 0, v15, vcc
	s_addc_u32 s11, s1, s11
	s_or_b32 s1, s38, 1
	global_load_dwordx4 v[50:53], v[84:85], off offset:16
	global_load_dwordx4 v[54:57], v[84:85], off
	global_load_dwordx4 v[58:61], v[10:11], off
	global_load_dwordx4 v[62:65], v[2:3], off offset:16
	s_nop 0
	global_load_dwordx4 v[2:5], v[14:15], off offset:16
	global_load_dwordx4 v[6:9], v[14:15], off
	global_load_dwordx4 v[66:69], v[84:85], off offset:2064
	global_load_dwordx4 v[70:73], v[84:85], off offset:2048
	global_load_dwordx4 v[74:77], v[10:11], off offset:2048
	global_load_dwordx4 v[78:81], v[12:13], off offset:16
	s_nop 0
	global_load_dwordx4 v[10:13], v[14:15], off offset:2064
	s_nop 0
	global_load_dwordx4 v[14:17], v[14:15], off offset:2048
	s_nop 0
	global_load_dwordx4 v[18:21], v0, s[10:11] offset:16
	global_load_dwordx4 v[22:25], v0, s[10:11]
	global_load_dwordx4 v[26:29], v0, s[10:11] offset:2064
	global_load_dwordx4 v[30:33], v0, s[10:11] offset:2048
	s_ashr_i32 s10, s1, 31
	s_add_i32 s38, s38, 0xffff0001
	s_cmp_lt_i32 s1, 0x10000
	s_cselect_b32 s11, s10, 0
	s_cselect_b32 s10, s1, s38
	s_cselect_b32 s1, s41, s43
	s_cselect_b32 s34, s40, s42
	s_lshl_b64 s[10:11], s[10:11], 12
	s_add_u32 s10, s34, s10
	s_addc_u32 s11, s1, s11
	global_load_dwordx4 v[34:37], v0, s[10:11] offset:16
	global_load_dwordx4 v[38:41], v0, s[10:11]
	global_load_dwordx4 v[42:45], v0, s[10:11] offset:2064
	global_load_dwordx4 v[46:49], v0, s[10:11] offset:2048
	s_or_b32 s0, s0, s2
	s_ashr_i32 s1, s0, 31
	s_lshl_b64 s[10:11], s[0:1], 11
	v_lshl_add_u64 v[104:105], v[86:87], 0, s[10:11]
	s_or_b32 s34, s3, s2
	s_mov_b64 s[2:3], 0
	s_mov_b32 s6, 0x3a800000
	v_readlane_b32 s44, v247, 37
	v_readlane_b32 s45, v247, 38
	v_readlane_b32 s46, v247, 39
	v_readlane_b32 s47, v247, 40
	v_readlane_b32 s48, v247, 41
	v_readlane_b32 s49, v247, 42
	v_readlane_b32 s50, v247, 43
	v_readlane_b32 s51, v247, 44
	v_readlane_b32 s52, v247, 45
	v_readlane_b32 s53, v247, 46
	v_readlane_b32 s54, v247, 47
	v_readlane_b32 s55, v247, 48
	s_waitcnt vmcnt(17)
	v_pk_add_f32 v[60:61], v[60:61], 1.0 op_sel_hi:[1,0]
	s_waitcnt vmcnt(16)
	v_pk_add_f32 v[64:65], v[64:65], 1.0 op_sel_hi:[1,0]
	v_pk_add_f32 v[62:63], v[62:63], 1.0 op_sel_hi:[1,0]
	s_waitcnt vmcnt(10)
	v_pk_add_f32 v[80:81], v[80:81], 1.0 op_sel_hi:[1,0]
	v_pk_add_f32 v[78:79], v[78:79], 1.0 op_sel_hi:[1,0]
	v_pk_add_f32 v[58:59], v[58:59], 1.0 op_sel_hi:[1,0]
	v_pk_add_f32 v[76:77], v[76:77], 1.0 op_sel_hi:[1,0]
	v_pk_add_f32 v[74:75], v[74:75], 1.0 op_sel_hi:[1,0]
	v_pk_mul_f32 v[88:89], v[52:53], v[64:65]
	v_pk_mul_f32 v[90:91], v[50:51], v[62:63]
	v_pk_mul_f32 v[92:93], v[68:69], v[80:81]
	v_pk_mul_f32 v[94:95], v[56:57], v[60:61]
	v_pk_mul_f32 v[96:97], v[54:55], v[58:59]
	v_pk_mul_f32 v[98:99], v[72:73], v[76:77]
	v_pk_mul_f32 v[100:101], v[70:71], v[74:75]
	v_pk_mul_f32 v[102:103], v[66:67], v[78:79]
	s_branch .LBB0_106

; __device__ __forceinline__ unsigned cvt_pk_bf16(float lo, float hi) { unsigned r; asm volatile("v_cvt_pk_bf16_f32 %0, %1, %2" : "=v"(r) : "v"(lo), "v"(hi)); return r; }
; __device__ __forceinline__ f32x4 inv4_1p_exp2(f32x4 t) {
;     f32x4 d;
; #pragma unroll
;     for (int i = 0; i < 4; ++i) d[i] = 1.0f + __builtin_amdgcn_exp2f(fminf(t[i], 30.0f));
;     const float p01 = d[0] * d[1], p23 = d[2] * d[3], r = __builtin_amdgcn_rcpf(p01 * p23), r01 = r * p23, r23 = r * p01;
;     return (f32x4){r01 * d[1], r01 * d[0], r23 * d[3], r23 * d[2]};
; }
; __device__ __forceinline__ f32x4 gelu_tanh4(f32x4 x) { const f32x4 u = (x + (x * x * x) * 0.044715f) * (-2.885390081777927f * 0.7978845608028654f); return x * inv4_1p_exp2(u); }
;     __device__ __forceinline__ void operator()(const f32x4 (&acc)[2][2][4][2], const Unit& u, int wr, int wc, int fr, int fq) const {
;         const int row0 = u.pm * BM + wr * 64 + fr; const int col0 = u.pn * BM + wc * 32 + 8 * fq;
;         f32x4 bv[2][2];
; #pragma unroll
;         for (int bj = 0; bj < 2; ++bj)
; #pragma unroll
;             for (int n = 0; n < 2; ++n) bv[bj][n] = *(const f32x4*)(bias + col0 + bj * HALF + 4 * n);
; #pragma unroll
;         for (int ai = 0; ai < 2; ++ai)
; #pragma unroll
;             for (int m = 0; m < 4; ++m) { bf16_t* rowp = O + (size_t)(row0 + ai * HALF + m * 16) * ldc + col0;
;                 float s1 = 0.f, s2 = 0.f;
; #pragma unroll
;                 for (int bj = 0; bj < 2; ++bj) { f32x4 v0 = acc[ai][bj][m][0] + bv[bj][0], v1 = acc[ai][bj][m][1] + bv[bj][1];
;                     v0 = gelu_tanh4(v0); v1 = gelu_tanh4(v1);
;                     s1 += ((v0[0] + v0[1]) + (v0[2] + v0[3])) + ((v1[0] + v1[1]) + (v1[2] + v1[3]));
;                     s2 += ((v0[0] * v0[0] + v0[1] * v0[1]) + (v0[2] * v0[2] + v0[3] * v0[3])) + ((v1[0] * v1[0] + v1[1] * v1[1]) + (v1[2] * v1[2] + v1[3] * v1[3]));
;                     u32x4 w; w.x = cvt_pk_bf16(v0[0], v0[1]); w.y = cvt_pk_bf16(v0[2], v0[3]); w.z = cvt_pk_bf16(v1[0], v1[1]); w.w = cvt_pk_bf16(v1[2], v1[3]);
;                     *(u32x4*)(rowp + bj * HALF) = w; }
.LBB0_584:
	s_lshl_b32 s10, s4, 8
	v_or_b32_e32 v166, s10, v174
	v_readlane_b32 s2, v246, 21
	v_ashrrev_i32_e32 v167, 31, v166
	v_readlane_b32 s3, v246, 22
	s_mov_b32 s6, 0xc0135761
	v_lshl_add_u32 v168, s33, 8, v172
	v_lshl_add_u64 v[38:39], v[166:167], 2, s[2:3]
	global_load_dwordx4 v[42:45], v[38:39], off offset:16
	global_load_dwordx4 v[46:49], v[38:39], off
	global_load_dwordx4 v[34:37], v[38:39], off offset:528
	s_nop 0
	global_load_dwordx4 v[38:41], v[38:39], off offset:512
	s_mov_b32 s2, 0x3d372713
	v_ashrrev_i32_e32 v169, 31, v168
	v_lshlrev_b64 v[170:171], 12, v[168:169]
	v_lshl_add_u64 v[170:171], s[84:85], 0, v[170:171]
	v_lshl_add_u64 v[170:171], v[166:167], 1, v[170:171]
	s_cmp_gt_i32 s4, 3
	s_waitcnt vmcnt(0)
	v_pk_add_f32 v[176:177], v[140:141], v[44:45]
	v_pk_add_f32 v[144:145], v[144:145], v[48:49]
	v_pk_add_f32 v[142:143], v[142:143], v[46:47]
	v_pk_add_f32 v[178:179], v[138:139], v[42:43]
	v_pk_mul_f32 v[138:139], v[144:145], v[144:145]
	v_pk_mul_f32 v[140:141], v[142:143], v[142:143]
	v_pk_mul_f32 v[138:139], v[144:145], v[138:139]
	v_pk_mul_f32 v[140:141], v[142:143], v[140:141]
	v_pk_fma_f32 v[138:139], v[138:139], s[2:3], v[144:145] op_sel_hi:[1,0,1]
	v_pk_fma_f32 v[140:141], v[140:141], s[2:3], v[142:143] op_sel_hi:[1,0,1]
	v_pk_mul_f32 v[138:139], v[138:139], s[6:7] op_sel_hi:[1,0]
	v_pk_mul_f32 v[140:141], v[140:141], s[6:7] op_sel_hi:[1,0]
	v_min_f32_e32 v138, 0x41f00000, v138
	v_min_f32_e32 v140, 0x41f00000, v140
	v_exp_f32_e32 v181, v140
	v_min_f32_e32 v140, 0x41f00000, v141
	v_exp_f32_e32 v141, v138
	v_min_f32_e32 v138, 0x41f00000, v139
	v_exp_f32_e32 v180, v140
	v_exp_f32_e32 v140, v138
	v_pk_add_f32 v[136:137], v[136:137], v[40:41]
	v_pk_add_f32 v[134:135], v[134:135], v[38:39]
	v_pk_add_f32 v[138:139], v[180:181], 1.0 op_sel_hi:[1,0]
	v_pk_add_f32 v[140:141], v[140:141], 1.0 op_sel_hi:[1,0]
	v_mul_f32_e32 v180, v139, v138
	v_mul_f32_e32 v181, v141, v140
	v_pk_add_f32 v[132:133], v[132:133], v[36:37]
	v_mul_f32_e32 v182, v180, v181
	v_rcp_f32_e32 v183, v182
	v_pk_add_f32 v[130:131], v[130:131], v[34:35]
	v_mul_f32_e32 v182, v181, v183
	v_mul_f32_e32 v180, v180, v183
	v_pk_mul_f32 v[182:183], v[138:139], v[182:183] op_sel_hi:[1,0]
	v_pk_mul_f32 v[138:139], v[140:141], v[180:181] op_sel_hi:[1,0]
	v_pk_mul_f32 v[140:141], v[142:143], v[182:183]
	v_pk_mul_f32 v[138:139], v[144:145], v[138:139]
	v_pk_mul_f32 v[142:143], v[176:177], v[176:177]
	v_pk_mul_f32 v[144:145], v[178:179], v[178:179]
	v_pk_mul_f32 v[142:143], v[176:177], v[142:143]
	v_pk_mul_f32 v[144:145], v[178:179], v[144:145]
	v_pk_fma_f32 v[142:143], v[142:143], s[2:3], v[176:177] op_sel_hi:[1,0,1]
	v_pk_fma_f32 v[144:145], v[144:145], s[2:3], v[178:179] op_sel_hi:[1,0,1]
	v_pk_mul_f32 v[142:143], v[142:143], s[6:7] op_sel_hi:[1,0]
	v_pk_mul_f32 v[144:145], v[144:145], s[6:7] op_sel_hi:[1,0]
	v_min_f32_e32 v142, 0x41f00000, v142
	v_min_f32_e32 v144, 0x41f00000, v144
	v_exp_f32_e32 v181, v144
	v_min_f32_e32 v144, 0x41f00000, v145
	v_exp_f32_e32 v145, v142
	v_min_f32_e32 v142, 0x41f00000, v143
	v_exp_f32_e32 v180, v144
	v_exp_f32_e32 v144, v142
	v_pk_add_f32 v[142:143], v[180:181], 1.0 op_sel_hi:[1,0]
	v_pk_add_f32 v[144:145], v[144:145], 1.0 op_sel_hi:[1,0]
	v_mul_f32_e32 v180, v143, v142
	v_mul_f32_e32 v181, v145, v144
	s_nop 0
	v_mul_f32_e32 v182, v180, v181
	v_rcp_f32_e32 v183, v182
	s_nop 0
	v_mul_f32_e32 v182, v181, v183
	v_mul_f32_e32 v180, v180, v183
	v_pk_mul_f32 v[182:183], v[142:143], v[182:183] op_sel_hi:[1,0]
	v_pk_mul_f32 v[142:143], v[144:145], v[180:181] op_sel_hi:[1,0]
	v_pk_mul_f32 v[144:145], v[178:179], v[182:183]
	v_pk_mul_f32 v[142:143], v[176:177], v[142:143]
	v_cvt_pk_bf16_f32 v176, v140, v141
	v_cvt_pk_bf16_f32 v177, v138, v139
	v_cvt_pk_bf16_f32 v178, v144, v145
	s_nop 0
	v_cvt_pk_bf16_f32 v179, v142, v143
	global_store_dwordx4 v[170:171], v[176:179], off
	s_nop 1
	v_pk_mul_f32 v[176:177], v[136:137], v[136:137]
	v_pk_mul_f32 v[178:179], v[134:135], v[134:135]
	v_pk_mul_f32 v[176:177], v[136:137], v[176:177]
	v_pk_mul_f32 v[178:179], v[134:135], v[178:179]
	v_pk_fma_f32 v[176:177], v[176:177], s[2:3], v[136:137] op_sel_hi:[1,0,1]
	v_pk_fma_f32 v[178:179], v[178:179], s[2:3], v[134:135] op_sel_hi:[1,0,1]
	v_pk_mul_f32 v[176:177], v[176:177], s[6:7] op_sel_hi:[1,0]
	v_pk_mul_f32 v[178:179], v[178:179], s[6:7] op_sel_hi:[1,0]
	v_min_f32_e32 v176, 0x41f00000, v176
	v_min_f32_e32 v178, 0x41f00000, v178
	v_exp_f32_e32 v181, v178
	v_min_f32_e32 v178, 0x41f00000, v179
	v_exp_f32_e32 v179, v176
	v_min_f32_e32 v176, 0x41f00000, v177
	v_exp_f32_e32 v180, v178
	v_exp_f32_e32 v178, v176
	v_pk_add_f32 v[176:177], v[180:181], 1.0 op_sel_hi:[1,0]
	v_pk_add_f32 v[178:179], v[178:179], 1.0 op_sel_hi:[1,0]
	v_mul_f32_e32 v180, v177, v176
	v_mul_f32_e32 v181, v179, v178
	s_nop 0
	v_mul_f32_e32 v182, v180, v181
	v_rcp_f32_e32 v183, v182
	s_nop 0
	v_mul_f32_e32 v182, v181, v183
	v_mul_f32_e32 v180, v180, v183
	v_pk_mul_f32 v[176:177], v[176:177], v[182:183] op_sel_hi:[1,0]
	v_pk_mul_f32 v[178:179], v[178:179], v[180:181] op_sel_hi:[1,0]
	v_pk_mul_f32 v[134:135], v[134:135], v[176:177]
	v_pk_mul_f32 v[136:137], v[136:137], v[178:179]
	v_pk_mul_f32 v[176:177], v[132:133], v[132:133]
	v_pk_mul_f32 v[178:179], v[130:131], v[130:131]
	v_pk_mul_f32 v[176:177], v[132:133], v[176:177]
	v_pk_mul_f32 v[178:179], v[130:131], v[178:179]
	v_pk_fma_f32 v[176:177], v[176:177], s[2:3], v[132:133] op_sel_hi:[1,0,1]
	v_pk_fma_f32 v[178:179], v[178:179], s[2:3], v[130:131] op_sel_hi:[1,0,1]
	v_pk_mul_f32 v[176:177], v[176:177], s[6:7] op_sel_hi:[1,0]
	v_pk_mul_f32 v[178:179], v[178:179], s[6:7] op_sel_hi:[1,0]
	v_min_f32_e32 v176, 0x41f00000, v176
	v_min_f32_e32 v178, 0x41f00000, v178
	v_exp_f32_e32 v181, v178
	v_min_f32_e32 v178, 0x41f00000, v179
	v_exp_f32_e32 v179, v176
	v_min_f32_e32 v176, 0x41f00000, v177
	v_exp_f32_e32 v180, v178
	v_exp_f32_e32 v178, v176
	s_cselect_b64 s[2:3], -1, 0
	s_cmp_lt_i32 s4, 4
	v_pk_add_f32 v[176:177], v[180:181], 1.0 op_sel_hi:[1,0]
	v_pk_add_f32 v[178:179], v[178:179], 1.0 op_sel_hi:[1,0]
	v_mul_f32_e32 v180, v177, v176
	v_mul_f32_e32 v181, v179, v178
	s_nop 0
	v_mul_f32_e32 v182, v180, v181
	v_rcp_f32_e32 v183, v182
	s_nop 0
	v_mul_f32_e32 v182, v181, v183
	v_mul_f32_e32 v180, v180, v183
	v_pk_mul_f32 v[176:177], v[176:177], v[182:183] op_sel_hi:[1,0]
	v_pk_mul_f32 v[178:179], v[178:179], v[180:181] op_sel_hi:[1,0]
	v_pk_mul_f32 v[130:131], v[130:131], v[176:177]
	v_pk_mul_f32 v[132:133], v[132:133], v[178:179]
	v_cvt_pk_bf16_f32 v176, v134, v135
	v_cvt_pk_bf16_f32 v177, v136, v137
	v_cvt_pk_bf16_f32 v178, v130, v131
	s_nop 0
	v_cvt_pk_bf16_f32 v179, v132, v133
	global_store_dwordx4 v[170:171], v[176:179], off offset:256
	s_cbranch_scc1 .LBB0_588
; __device__ __forceinline__ unsigned cvt_pk_bf16(float lo, float hi) { unsigned r; asm volatile("v_cvt_pk_bf16_f32 %0, %1, %2" : "=v"(r) : "v"(lo), "v"(hi)); return r; }
;     __device__ __forceinline__ void operator()(const f32x4 (&acc)[2][2][4][2], const Unit& u, int wr, int wc, int fr, int fq) const {
;     ...
;                     s1 += ((v0[0] + v0[1]) + (v0[2] + v0[3])) + ((v1[0] + v1[1]) + (v1[2] + v1[3]));
;                     s2 += ((v0[0] * v0[0] + v0[1] * v0[1]) + (v0[2] * v0[2] + v0[3] * v0[3])) + ((v1[0] * v1[0] + v1[1] * v1[1]) + (v1[2] * v1[2] + v1[3] * v1[3]));
;                     u32x4 w; w.x = cvt_pk_bf16(v0[0], v0[1]); w.y = cvt_pk_bf16(v0[2], v0[3]); w.z = cvt_pk_bf16(v1[0], v1[1]); w.w = cvt_pk_bf16(v1[2], v1[3]);
;                     *(u32x4*)(rowp + bj * HALF) = w; }
;                 if (u.pn * BM >= stat_col0) {
;                     s1 += __shfl_xor(s1, 16); s1 += __shfl_xor(s1, 32); s2 += __shfl_xor(s2, 16); s2 += __shfl_xor(s2, 32);
;                     if (fq == 0) { float* sp = stats + (size_t)(row0 + ai * HALF + m * 16) * 32 + (((u.pn * BM - stat_col0) >> 8) * 4 + wc) * 2; sp[0] = s1; sp[1] = s2; } } }
	v_mul_f32_e32 v181, v139, v139
	v_add_f32_e32 v192, v138, v139
	v_and_b32_e32 v139, 64, v203
	v_mul_f32_e32 v179, v138, v138
	v_mul_f32_e32 v187, v142, v142
	v_pk_mul_f32 v[198:199], v[132:133], v[132:133]
	v_pk_mul_f32 v[200:201], v[130:131], v[130:131]
	v_add_f32_e32 v196, v142, v143
	v_xor_b32_e32 v138, 16, v203
	v_add_u32_e32 v142, 64, v139
	v_mov_b32_e32 v214, v200
	v_mov_b32_e32 v215, v199
	v_pk_mov_b32 v[198:199], v[200:201], v[198:199] op_sel:[1,0]
	v_cmp_lt_i32_e32 vcc, v138, v142
	v_mul_f32_e32 v171, v140, v140
	v_mul_f32_e32 v177, v141, v141
	v_mul_f32_e32 v183, v144, v144
	v_mul_f32_e32 v185, v145, v145
	v_mul_f32_e32 v189, v143, v143
	v_mul_f32_e32 v191, v134, v134
	v_mul_f32_e32 v193, v135, v135
	v_mul_f32_e32 v195, v136, v136
	v_mul_f32_e32 v197, v137, v137
	v_pk_add_f32 v[198:199], v[198:199], v[214:215]
	v_add_f32_e32 v190, v140, v141
	v_add_f32_e32 v194, v144, v145
	v_cndmask_b32_e32 v138, v203, v138, vcc
	v_mov_b32_e32 v170, v134
	v_mov_b32_e32 v176, v135
	v_mov_b32_e32 v178, v136
	v_mov_b32_e32 v180, v137
	v_mov_b32_e32 v182, v130
	v_mov_b32_e32 v184, v131
	v_mov_b32_e32 v186, v132
	v_mov_b32_e32 v188, v133
	v_pk_add_f32 v[198:199], v[198:199], v[198:199] op_sel_hi:[0,1]
	v_lshlrev_b32_e32 v143, 2, v138
	v_pk_add_f32 v[138:139], v[190:191], v[192:193]
	v_pk_add_f32 v[140:141], v[194:195], v[196:197]
	v_pk_add_f32 v[134:135], v[170:171], v[176:177]
	v_pk_add_f32 v[136:137], v[178:179], v[180:181]
	v_pk_add_f32 v[130:131], v[182:183], v[184:185]
	v_pk_add_f32 v[132:133], v[186:187], v[188:189]
	v_pk_add_f32 v[138:139], v[138:139], v[140:141]
	v_mov_b32_e32 v198, v1
	v_pk_add_f32 v[134:135], v[134:135], v[136:137]
	v_pk_add_f32 v[130:131], v[130:131], v[132:133]
	v_pk_add_f32 v[138:139], v[138:139], v[198:199]
	v_pk_add_f32 v[130:131], v[134:135], v[130:131]
	v_xor_b32_e32 v134, 32, v203
	v_pk_add_f32 v[130:131], v[130:131], v[138:139]
	ds_bpermute_b32 v132, v143, v130
	ds_bpermute_b32 v133, v143, v131
	v_cmp_lt_i32_e32 vcc, v134, v142
	s_waitcnt lgkmcnt(0)
	v_pk_add_f32 v[130:131], v[130:131], v[132:133]
	v_cndmask_b32_e32 v134, v203, v134, vcc
	v_lshlrev_b32_e32 v134, 2, v134
	ds_bpermute_b32 v132, v134, v130
	ds_bpermute_b32 v133, v134, v131
	s_and_saveexec_b64 s[8:9], s[36:37]
	s_cbranch_execz .LBB0_587
	s_add_i32 s4, s10, 0xfffffc00
	s_lshr_b32 s4, s4, 6
	v_readlane_b32 s34, v248, 10
	v_lshlrev_b64 v[134:135], 7, v[168:169]
	s_or_b32 s4, s4, s59
	v_readlane_b32 s35, v248, 11
	v_lshl_add_u64 v[134:135], s[86:87], 0, v[134:135]
	s_lshl_b32 s34, s4, 3
	s_mov_b32 s5, s35
	v_writelane_b32 v248, s4, 10
	v_lshl_add_u64 v[134:135], v[134:135], 0, s[34:35]
	s_waitcnt lgkmcnt(0)
	v_pk_add_f32 v[130:131], v[130:131], v[132:133]
	v_writelane_b32 v248, s5, 11
	global_store_dwordx2 v[134:135], v[130:131], off

; __device__ __forceinline__ unsigned cvt_pk_bf16(float lo, float hi) { unsigned r; asm volatile("v_cvt_pk_bf16_f32 %0, %1, %2" : "=v"(r) : "v"(lo), "v"(hi)); return r; }
; __device__ __forceinline__ f32x4 inv4_1p_exp2(f32x4 t) {
;     f32x4 d;
; #pragma unroll
;     for (int i = 0; i < 4; ++i) d[i] = 1.0f + __builtin_amdgcn_exp2f(fminf(t[i], 30.0f));
;     const float p01 = d[0] * d[1], p23 = d[2] * d[3], r = __builtin_amdgcn_rcpf(p01 * p23), r01 = r * p23, r23 = r * p01;
;     return (f32x4){r01 * d[1], r01 * d[0], r23 * d[3], r23 * d[2]};
; }
; __device__ __forceinline__ f32x4 gelu_tanh4(f32x4 x) { const f32x4 u = (x + (x * x * x) * 0.044715f) * (-2.885390081777927f * 0.7978845608028654f); return x * inv4_1p_exp2(u); }
;     __device__ __forceinline__ void operator()(const f32x4 (&acc)[2][2][4][2], const Unit& u, int wr, int wc, int fr, int fq) const {
;     ...
;             for (int m = 0; m < 4; ++m) { bf16_t* rowp = O + (size_t)(row0 + ai * HALF + m * 16) * ldc + col0;
;                 float s1 = 0.f, s2 = 0.f;
; #pragma unroll
;                 for (int bj = 0; bj < 2; ++bj) { f32x4 v0 = acc[ai][bj][m][0] + bv[bj][0], v1 = acc[ai][bj][m][1] + bv[bj][1];
;                     v0 = gelu_tanh4(v0); v1 = gelu_tanh4(v1);
;                     s1 += ((v0[0] + v0[1]) + (v0[2] + v0[3])) + ((v1[0] + v1[1]) + (v1[2] + v1[3]));
;                     s2 += ((v0[0] * v0[0] + v0[1] * v0[1]) + (v0[2] * v0[2] + v0[3] * v0[3])) + ((v1[0] * v1[0] + v1[1] * v1[1]) + (v1[2] * v1[2] + v1[3] * v1[3]));
;                     u32x4 w; w.x = cvt_pk_bf16(v0[0], v0[1]); w.y = cvt_pk_bf16(v0[2], v0[3]); w.z = cvt_pk_bf16(v1[0], v1[1]); w.w = cvt_pk_bf16(v1[2], v1[3]);
;                     *(u32x4*)(rowp + bj * HALF) = w; }
.LBB0_588:
	v_pk_add_f32 v[128:129], v[128:129], v[48:49]
	v_pk_add_f32 v[126:127], v[126:127], v[46:47]
	v_pk_add_f32 v[134:135], v[124:125], v[44:45]
	v_pk_add_f32 v[136:137], v[122:123], v[42:43]
	v_pk_mul_f32 v[122:123], v[128:129], v[128:129]
	v_pk_mul_f32 v[124:125], v[126:127], v[126:127]
	v_pk_mul_f32 v[122:123], v[128:129], v[122:123]
	v_pk_mul_f32 v[124:125], v[126:127], v[124:125]
	s_mov_b32 s4, 0x3d372713
	v_pk_fma_f32 v[122:123], v[122:123], s[4:5], v[128:129] op_sel_hi:[1,0,1]
	v_pk_fma_f32 v[124:125], v[124:125], s[4:5], v[126:127] op_sel_hi:[1,0,1]
	v_pk_mul_f32 v[122:123], v[122:123], s[6:7] op_sel_hi:[1,0]
	v_pk_mul_f32 v[124:125], v[124:125], s[6:7] op_sel_hi:[1,0]
	v_min_f32_e32 v122, 0x41f00000, v122
	v_min_f32_e32 v124, 0x41f00000, v124
	v_exp_f32_e32 v139, v124
	v_min_f32_e32 v124, 0x41f00000, v125
	v_exp_f32_e32 v125, v122
	v_min_f32_e32 v122, 0x41f00000, v123
	v_exp_f32_e32 v138, v124
	v_exp_f32_e32 v124, v122
	v_or_b32_e32 v130, 16, v168
	v_ashrrev_i32_e32 v131, 31, v130
	v_pk_add_f32 v[122:123], v[138:139], 1.0 op_sel_hi:[1,0]
	v_pk_add_f32 v[124:125], v[124:125], 1.0 op_sel_hi:[1,0]
	v_mul_f32_e32 v138, v123, v122
	v_mul_f32_e32 v139, v125, v124
	s_waitcnt lgkmcnt(0)
	v_lshlrev_b64 v[132:133], 12, v[130:131]
	v_mul_f32_e32 v140, v138, v139
	v_rcp_f32_e32 v141, v140
	v_lshl_add_u64 v[132:133], s[84:85], 0, v[132:133]
	v_lshl_add_u64 v[132:133], v[166:167], 1, v[132:133]
	v_pk_add_f32 v[120:121], v[120:121], v[40:41]
	v_mul_f32_e32 v140, v139, v141
	v_mul_f32_e32 v138, v138, v141
	v_pk_mul_f32 v[140:141], v[122:123], v[140:141] op_sel_hi:[1,0]
	v_pk_mul_f32 v[122:123], v[124:125], v[138:139] op_sel_hi:[1,0]
	v_pk_mul_f32 v[124:125], v[126:127], v[140:141]
	v_pk_mul_f32 v[122:123], v[128:129], v[122:123]
	v_pk_mul_f32 v[126:127], v[134:135], v[134:135]
	v_pk_mul_f32 v[128:129], v[136:137], v[136:137]
	v_pk_mul_f32 v[126:127], v[134:135], v[126:127]
	v_pk_mul_f32 v[128:129], v[136:137], v[128:129]
	v_pk_fma_f32 v[126:127], v[126:127], s[4:5], v[134:135] op_sel_hi:[1,0,1]
	v_pk_fma_f32 v[128:129], v[128:129], s[4:5], v[136:137] op_sel_hi:[1,0,1]
	v_pk_mul_f32 v[126:127], v[126:127], s[6:7] op_sel_hi:[1,0]
	v_pk_mul_f32 v[128:129], v[128:129], s[6:7] op_sel_hi:[1,0]
	v_min_f32_e32 v126, 0x41f00000, v126
	v_min_f32_e32 v128, 0x41f00000, v128
	v_exp_f32_e32 v139, v128
	v_min_f32_e32 v128, 0x41f00000, v129
	v_exp_f32_e32 v129, v126
	v_min_f32_e32 v126, 0x41f00000, v127
	v_exp_f32_e32 v138, v128
	v_exp_f32_e32 v128, v126
	v_pk_add_f32 v[118:119], v[118:119], v[38:39]
	s_andn2_b64 vcc, exec, s[2:3]
	v_pk_add_f32 v[126:127], v[138:139], 1.0 op_sel_hi:[1,0]
	v_pk_add_f32 v[128:129], v[128:129], 1.0 op_sel_hi:[1,0]
	v_mul_f32_e32 v138, v127, v126
	v_mul_f32_e32 v139, v129, v128
	s_nop 0
	v_mul_f32_e32 v140, v138, v139
	v_rcp_f32_e32 v141, v140
	s_nop 0
	v_mul_f32_e32 v140, v139, v141
	v_mul_f32_e32 v138, v138, v141
	v_pk_mul_f32 v[140:141], v[126:127], v[140:141] op_sel_hi:[1,0]
	v_pk_mul_f32 v[126:127], v[128:129], v[138:139] op_sel_hi:[1,0]
	v_pk_mul_f32 v[128:129], v[136:137], v[140:141]
	v_pk_mul_f32 v[126:127], v[134:135], v[126:127]
	v_cvt_pk_bf16_f32 v134, v124, v125
	v_cvt_pk_bf16_f32 v135, v122, v123
	v_cvt_pk_bf16_f32 v136, v128, v129
	s_nop 0
	v_cvt_pk_bf16_f32 v137, v126, v127
	global_store_dwordx4 v[132:133], v[134:137], off
	s_nop 1
	v_pk_add_f32 v[134:135], v[116:117], v[36:37]
	v_pk_add_f32 v[136:137], v[114:115], v[34:35]
	v_pk_mul_f32 v[114:115], v[120:121], v[120:121]
	v_pk_mul_f32 v[116:117], v[118:119], v[118:119]
	v_pk_mul_f32 v[114:115], v[120:121], v[114:115]
	v_pk_mul_f32 v[116:117], v[118:119], v[116:117]
	v_pk_fma_f32 v[114:115], v[114:115], s[4:5], v[120:121] op_sel_hi:[1,0,1]
	v_pk_fma_f32 v[116:117], v[116:117], s[4:5], v[118:119] op_sel_hi:[1,0,1]
	v_pk_mul_f32 v[114:115], v[114:115], s[6:7] op_sel_hi:[1,0]
	v_pk_mul_f32 v[116:117], v[116:117], s[6:7] op_sel_hi:[1,0]
	v_min_f32_e32 v114, 0x41f00000, v114
	v_min_f32_e32 v116, 0x41f00000, v116
	v_exp_f32_e32 v139, v116
	v_min_f32_e32 v116, 0x41f00000, v117
	v_exp_f32_e32 v117, v114
	v_min_f32_e32 v114, 0x41f00000, v115
	v_exp_f32_e32 v138, v116
	v_exp_f32_e32 v116, v114
	v_pk_add_f32 v[114:115], v[138:139], 1.0 op_sel_hi:[1,0]
	v_pk_add_f32 v[116:117], v[116:117], 1.0 op_sel_hi:[1,0]
	v_mul_f32_e32 v138, v115, v114
	v_mul_f32_e32 v139, v117, v116
	s_nop 0
	v_mul_f32_e32 v140, v138, v139
	v_rcp_f32_e32 v141, v140
	s_nop 0
	v_mul_f32_e32 v140, v139, v141
	v_mul_f32_e32 v138, v138, v141
	v_pk_mul_f32 v[140:141], v[114:115], v[140:141] op_sel_hi:[1,0]
	v_pk_mul_f32 v[114:115], v[116:117], v[138:139] op_sel_hi:[1,0]
	v_pk_mul_f32 v[116:117], v[118:119], v[140:141]
	v_pk_mul_f32 v[114:115], v[120:121], v[114:115]
	v_pk_mul_f32 v[118:119], v[134:135], v[134:135]
	v_pk_mul_f32 v[120:121], v[136:137], v[136:137]
	v_pk_mul_f32 v[118:119], v[134:135], v[118:119]
	v_pk_mul_f32 v[120:121], v[136:137], v[120:121]
	v_pk_fma_f32 v[118:119], v[118:119], s[4:5], v[134:135] op_sel_hi:[1,0,1]
	v_pk_fma_f32 v[120:121], v[120:121], s[4:5], v[136:137] op_sel_hi:[1,0,1]
	v_pk_mul_f32 v[118:119], v[118:119], s[6:7] op_sel_hi:[1,0]
	v_pk_mul_f32 v[120:121], v[120:121], s[6:7] op_sel_hi:[1,0]
	v_min_f32_e32 v118, 0x41f00000, v118
	v_min_f32_e32 v120, 0x41f00000, v120
	v_exp_f32_e32 v139, v120
	v_min_f32_e32 v120, 0x41f00000, v121
	v_exp_f32_e32 v121, v118
	v_min_f32_e32 v118, 0x41f00000, v119
	v_exp_f32_e32 v138, v120
	v_exp_f32_e32 v120, v118
	v_pk_add_f32 v[118:119], v[138:139], 1.0 op_sel_hi:[1,0]
	v_pk_add_f32 v[120:121], v[120:121], 1.0 op_sel_hi:[1,0]
	v_mul_f32_e32 v138, v119, v118
	v_mul_f32_e32 v139, v121, v120
	s_nop 0
	v_mul_f32_e32 v140, v138, v139
	v_rcp_f32_e32 v141, v140
	s_nop 0
	v_mul_f32_e32 v140, v139, v141
	v_mul_f32_e32 v138, v138, v141
	v_pk_mul_f32 v[140:141], v[118:119], v[140:141] op_sel_hi:[1,0]
	v_pk_mul_f32 v[118:119], v[120:121], v[138:139] op_sel_hi:[1,0]
	v_pk_mul_f32 v[120:121], v[136:137], v[140:141]
	v_pk_mul_f32 v[118:119], v[134:135], v[118:119]
	v_cvt_pk_bf16_f32 v134, v116, v117
	v_cvt_pk_bf16_f32 v135, v114, v115
	v_cvt_pk_bf16_f32 v136, v120, v121
	s_nop 0
	v_cvt_pk_bf16_f32 v137, v118, v119
	global_store_dwordx4 v[132:133], v[134:137], off offset:256
	v_cndmask_b32_e64 v132, 0, 1, s[2:3]
	v_cmp_ne_u32_e64 s[40:41], 1, v132
	s_cbranch_vccnz .LBB0_592
; __device__ __forceinline__ unsigned cvt_pk_bf16(float lo, float hi) { unsigned r; asm volatile("v_cvt_pk_bf16_f32 %0, %1, %2" : "=v"(r) : "v"(lo), "v"(hi)); return r; }
;     __device__ __forceinline__ void operator()(const f32x4 (&acc)[2][2][4][2], const Unit& u, int wr, int wc, int fr, int fq) const {
;     ...
;                     s1 += ((v0[0] + v0[1]) + (v0[2] + v0[3])) + ((v1[0] + v1[1]) + (v1[2] + v1[3]));
;                     s2 += ((v0[0] * v0[0] + v0[1] * v0[1]) + (v0[2] * v0[2] + v0[3] * v0[3])) + ((v1[0] * v1[0] + v1[1] * v1[1]) + (v1[2] * v1[2] + v1[3] * v1[3]));
;                     u32x4 w; w.x = cvt_pk_bf16(v0[0], v0[1]); w.y = cvt_pk_bf16(v0[2], v0[3]); w.z = cvt_pk_bf16(v1[0], v1[1]); w.w = cvt_pk_bf16(v1[2], v1[3]);
;                     *(u32x4*)(rowp + bj * HALF) = w; }
;                 if (u.pn * BM >= stat_col0) {
;                     s1 += __shfl_xor(s1, 16); s1 += __shfl_xor(s1, 32); s2 += __shfl_xor(s2, 16); s2 += __shfl_xor(s2, 32);
;                     if (fq == 0) { float* sp = stats + (size_t)(row0 + ai * HALF + m * 16) * 32 + (((u.pn * BM - stat_col0) >> 8) * 4 + wc) * 2; sp[0] = s1; sp[1] = s2; } } }
	v_mul_f32_e32 v139, v123, v123
	v_add_f32_e32 v178, v122, v123
	v_and_b32_e32 v123, 64, v203
	v_mul_f32_e32 v137, v122, v122
	v_mul_f32_e32 v145, v126, v126
	v_pk_mul_f32 v[184:185], v[118:119], v[118:119]
	v_pk_mul_f32 v[186:187], v[120:121], v[120:121]
	v_add_f32_e32 v182, v126, v127
	v_xor_b32_e32 v122, 16, v203
	v_add_u32_e32 v126, 64, v123
	v_mul_f32_e32 v133, v124, v124
	v_mul_f32_e32 v135, v125, v125
	v_mov_b32_e32 v188, v186
	v_mov_b32_e32 v189, v185
	v_pk_mov_b32 v[184:185], v[186:187], v[184:185] op_sel:[1,0]
	v_cmp_lt_i32_e32 vcc, v122, v126
	v_mov_b32_e32 v132, v116
	v_mov_b32_e32 v134, v117
	v_mov_b32_e32 v136, v114
	v_mov_b32_e32 v138, v115
	v_mul_f32_e32 v141, v128, v128
	v_mul_f32_e32 v143, v129, v129
	v_mul_f32_e32 v171, v127, v127
	v_mul_f32_e32 v177, v116, v116
	v_mul_f32_e32 v179, v117, v117
	v_mul_f32_e32 v181, v114, v114
	v_mul_f32_e32 v183, v115, v115
	v_pk_add_f32 v[184:185], v[184:185], v[188:189]
	v_add_f32_e32 v176, v124, v125
	v_add_f32_e32 v180, v128, v129
	v_cndmask_b32_e32 v122, v203, v122, vcc
	v_pk_add_f32 v[116:117], v[132:133], v[134:135]
	v_pk_add_f32 v[114:115], v[136:137], v[138:139]
	v_mov_b32_e32 v140, v120
	v_mov_b32_e32 v142, v121
	v_mov_b32_e32 v144, v118
	v_mov_b32_e32 v170, v119
	v_pk_add_f32 v[184:185], v[184:185], v[184:185] op_sel_hi:[0,1]
	v_lshlrev_b32_e32 v127, 2, v122
	v_pk_add_f32 v[122:123], v[176:177], v[178:179]
	v_pk_add_f32 v[124:125], v[180:181], v[182:183]
	v_pk_add_f32 v[114:115], v[116:117], v[114:115]
	v_pk_add_f32 v[116:117], v[140:141], v[142:143]
	v_pk_add_f32 v[118:119], v[144:145], v[170:171]
	v_pk_add_f32 v[122:123], v[122:123], v[124:125]
	v_mov_b32_e32 v184, v1
	v_pk_add_f32 v[116:117], v[116:117], v[118:119]
	v_pk_add_f32 v[122:123], v[122:123], v[184:185]
	v_pk_add_f32 v[114:115], v[114:115], v[116:117]
	v_xor_b32_e32 v118, 32, v203
	v_pk_add_f32 v[114:115], v[114:115], v[122:123]
	ds_bpermute_b32 v116, v127, v114
	ds_bpermute_b32 v117, v127, v115
	v_cmp_lt_i32_e32 vcc, v118, v126
	s_waitcnt lgkmcnt(0)
	v_pk_add_f32 v[114:115], v[114:115], v[116:117]
	v_cndmask_b32_e32 v118, v203, v118, vcc
	v_lshlrev_b32_e32 v118, 2, v118
	ds_bpermute_b32 v116, v118, v114
	ds_bpermute_b32 v117, v118, v115
	s_and_saveexec_b64 s[2:3], s[36:37]
	s_cbranch_execz .LBB0_591
	s_add_i32 s4, s10, 0xfffffc00
	s_lshr_b32 s4, s4, 6
	v_readlane_b32 s8, v248, 10
	v_lshlrev_b64 v[118:119], 7, v[130:131]
	s_or_b32 s4, s4, s59
	v_readlane_b32 s9, v248, 11
	v_lshl_add_u64 v[118:119], s[86:87], 0, v[118:119]
	s_lshl_b32 s8, s4, 3
	s_mov_b32 s5, s9
	v_writelane_b32 v248, s4, 10
	v_lshl_add_u64 v[118:119], v[118:119], 0, s[8:9]
	s_waitcnt lgkmcnt(0)
	v_pk_add_f32 v[114:115], v[114:115], v[116:117]
	v_writelane_b32 v248, s5, 11
	global_store_dwordx2 v[118:119], v[114:115], off

; __device__ __forceinline__ unsigned cvt_pk_bf16(float lo, float hi) { unsigned r; asm volatile("v_cvt_pk_bf16_f32 %0, %1, %2" : "=v"(r) : "v"(lo), "v"(hi)); return r; }
; __device__ __forceinline__ f32x4 inv4_1p_exp2(f32x4 t) {
;     f32x4 d;
; #pragma unroll
;     for (int i = 0; i < 4; ++i) d[i] = 1.0f + __builtin_amdgcn_exp2f(fminf(t[i], 30.0f));
;     const float p01 = d[0] * d[1], p23 = d[2] * d[3], r = __builtin_amdgcn_rcpf(p01 * p23), r01 = r * p23, r23 = r * p01;
;     return (f32x4){r01 * d[1], r01 * d[0], r23 * d[3], r23 * d[2]};
; }
; __device__ __forceinline__ f32x4 gelu_tanh4(f32x4 x) { const f32x4 u = (x + (x * x * x) * 0.044715f) * (-2.885390081777927f * 0.7978845608028654f); return x * inv4_1p_exp2(u); }
;     __device__ __forceinline__ void operator()(const f32x4 (&acc)[2][2][4][2], const Unit& u, int wr, int wc, int fr, int fq) const {
;     ...
;             for (int m = 0; m < 4; ++m) { bf16_t* rowp = O + (size_t)(row0 + ai * HALF + m * 16) * ldc + col0;
;                 float s1 = 0.f, s2 = 0.f;
; #pragma unroll
;                 for (int bj = 0; bj < 2; ++bj) { f32x4 v0 = acc[ai][bj][m][0] + bv[bj][0], v1 = acc[ai][bj][m][1] + bv[bj][1];
;                     v0 = gelu_tanh4(v0); v1 = gelu_tanh4(v1);
;                     s1 += ((v0[0] + v0[1]) + (v0[2] + v0[3])) + ((v1[0] + v1[1]) + (v1[2] + v1[3]));
;                     s2 += ((v0[0] * v0[0] + v0[1] * v0[1]) + (v0[2] * v0[2] + v0[3] * v0[3])) + ((v1[0] * v1[0] + v1[1] * v1[1]) + (v1[2] * v1[2] + v1[3] * v1[3]));
;                     u32x4 w; w.x = cvt_pk_bf16(v0[0], v0[1]); w.y = cvt_pk_bf16(v0[2], v0[3]); w.z = cvt_pk_bf16(v1[0], v1[1]); w.w = cvt_pk_bf16(v1[2], v1[3]);
;                     *(u32x4*)(rowp + bj * HALF) = w; }
.LBB0_592:
	v_pk_add_f32 v[112:113], v[112:113], v[48:49]
	v_pk_add_f32 v[110:111], v[110:111], v[46:47]
	v_pk_add_f32 v[118:119], v[108:109], v[44:45]
	v_pk_add_f32 v[120:121], v[106:107], v[42:43]
	v_pk_mul_f32 v[106:107], v[112:113], v[112:113]
	v_pk_mul_f32 v[108:109], v[110:111], v[110:111]
	v_pk_mul_f32 v[106:107], v[112:113], v[106:107]
	v_pk_mul_f32 v[108:109], v[110:111], v[108:109]
	s_mov_b32 s2, 0x3d372713
	v_pk_fma_f32 v[106:107], v[106:107], s[2:3], v[112:113] op_sel_hi:[1,0,1]
	v_pk_fma_f32 v[108:109], v[108:109], s[2:3], v[110:111] op_sel_hi:[1,0,1]
	s_mov_b32 s4, 0xc0135761
	v_pk_mul_f32 v[106:107], v[106:107], s[4:5] op_sel_hi:[1,0]
	v_pk_mul_f32 v[108:109], v[108:109], s[4:5] op_sel_hi:[1,0]
	v_min_f32_e32 v106, 0x41f00000, v106
	v_min_f32_e32 v108, 0x41f00000, v108
	v_exp_f32_e32 v123, v108
	v_min_f32_e32 v108, 0x41f00000, v109
	v_exp_f32_e32 v109, v106
	v_min_f32_e32 v106, 0x41f00000, v107
	v_exp_f32_e32 v122, v108
	v_exp_f32_e32 v108, v106
	v_or_b32_e32 v114, 32, v168
	v_ashrrev_i32_e32 v115, 31, v114
	v_pk_add_f32 v[106:107], v[122:123], 1.0 op_sel_hi:[1,0]
	v_pk_add_f32 v[108:109], v[108:109], 1.0 op_sel_hi:[1,0]
	v_mul_f32_e32 v122, v107, v106
	v_mul_f32_e32 v123, v109, v108
	s_waitcnt lgkmcnt(0)
	v_lshlrev_b64 v[116:117], 12, v[114:115]
	v_mul_f32_e32 v124, v122, v123
	v_rcp_f32_e32 v125, v124
	v_lshl_add_u64 v[116:117], s[84:85], 0, v[116:117]
	v_lshl_add_u64 v[116:117], v[166:167], 1, v[116:117]
	v_pk_add_f32 v[104:105], v[104:105], v[40:41]
	v_mul_f32_e32 v124, v123, v125
	v_mul_f32_e32 v122, v122, v125
	v_pk_mul_f32 v[124:125], v[106:107], v[124:125] op_sel_hi:[1,0]
	v_pk_mul_f32 v[106:107], v[108:109], v[122:123] op_sel_hi:[1,0]
	v_pk_mul_f32 v[108:109], v[110:111], v[124:125]
	v_pk_mul_f32 v[106:107], v[112:113], v[106:107]
	v_pk_mul_f32 v[110:111], v[118:119], v[118:119]
	v_pk_mul_f32 v[112:113], v[120:121], v[120:121]
	v_pk_mul_f32 v[110:111], v[118:119], v[110:111]
	v_pk_mul_f32 v[112:113], v[120:121], v[112:113]
	v_pk_fma_f32 v[110:111], v[110:111], s[2:3], v[118:119] op_sel_hi:[1,0,1]
	v_pk_fma_f32 v[112:113], v[112:113], s[2:3], v[120:121] op_sel_hi:[1,0,1]
	v_pk_mul_f32 v[110:111], v[110:111], s[4:5] op_sel_hi:[1,0]
	v_pk_mul_f32 v[112:113], v[112:113], s[4:5] op_sel_hi:[1,0]
	v_min_f32_e32 v110, 0x41f00000, v110
	v_min_f32_e32 v112, 0x41f00000, v112
	v_exp_f32_e32 v123, v112
	v_min_f32_e32 v112, 0x41f00000, v113
	v_exp_f32_e32 v113, v110
	v_min_f32_e32 v110, 0x41f00000, v111
	v_exp_f32_e32 v122, v112
	v_exp_f32_e32 v112, v110
	v_pk_add_f32 v[102:103], v[102:103], v[38:39]
	s_and_b64 vcc, exec, s[40:41]
	v_pk_add_f32 v[110:111], v[122:123], 1.0 op_sel_hi:[1,0]
	v_pk_add_f32 v[112:113], v[112:113], 1.0 op_sel_hi:[1,0]
	v_mul_f32_e32 v122, v111, v110
	v_mul_f32_e32 v123, v113, v112
	s_nop 0
	v_mul_f32_e32 v124, v122, v123
	v_rcp_f32_e32 v125, v124
	s_nop 0
	v_mul_f32_e32 v124, v123, v125
	v_mul_f32_e32 v122, v122, v125
	v_pk_mul_f32 v[124:125], v[110:111], v[124:125] op_sel_hi:[1,0]
	v_pk_mul_f32 v[110:111], v[112:113], v[122:123] op_sel_hi:[1,0]
	v_pk_mul_f32 v[112:113], v[120:121], v[124:125]
	v_pk_mul_f32 v[110:111], v[118:119], v[110:111]
	v_cvt_pk_bf16_f32 v118, v108, v109
	v_cvt_pk_bf16_f32 v119, v106, v107
	v_cvt_pk_bf16_f32 v120, v112, v113
	s_nop 0
	v_cvt_pk_bf16_f32 v121, v110, v111
	global_store_dwordx4 v[116:117], v[118:121], off
	s_nop 1
	v_pk_add_f32 v[118:119], v[100:101], v[36:37]
	v_pk_add_f32 v[120:121], v[98:99], v[34:35]
	v_pk_mul_f32 v[98:99], v[104:105], v[104:105]
	v_pk_mul_f32 v[100:101], v[102:103], v[102:103]
	v_pk_mul_f32 v[98:99], v[104:105], v[98:99]
	v_pk_mul_f32 v[100:101], v[102:103], v[100:101]
	v_pk_fma_f32 v[98:99], v[98:99], s[2:3], v[104:105] op_sel_hi:[1,0,1]
	v_pk_fma_f32 v[100:101], v[100:101], s[2:3], v[102:103] op_sel_hi:[1,0,1]
	v_pk_mul_f32 v[98:99], v[98:99], s[4:5] op_sel_hi:[1,0]
	v_pk_mul_f32 v[100:101], v[100:101], s[4:5] op_sel_hi:[1,0]
	v_min_f32_e32 v98, 0x41f00000, v98
	v_min_f32_e32 v100, 0x41f00000, v100
	v_exp_f32_e32 v123, v100
	v_min_f32_e32 v100, 0x41f00000, v101
	v_exp_f32_e32 v101, v98
	v_min_f32_e32 v98, 0x41f00000, v99
	v_exp_f32_e32 v122, v100
	v_exp_f32_e32 v100, v98
	v_pk_add_f32 v[98:99], v[122:123], 1.0 op_sel_hi:[1,0]
	v_pk_add_f32 v[100:101], v[100:101], 1.0 op_sel_hi:[1,0]
	v_mul_f32_e32 v122, v99, v98
	v_mul_f32_e32 v123, v101, v100
	s_nop 0
	v_mul_f32_e32 v124, v122, v123
	v_rcp_f32_e32 v125, v124
	s_nop 0
	v_mul_f32_e32 v124, v123, v125
	v_mul_f32_e32 v122, v122, v125
	v_pk_mul_f32 v[124:125], v[98:99], v[124:125] op_sel_hi:[1,0]
	v_pk_mul_f32 v[98:99], v[100:101], v[122:123] op_sel_hi:[1,0]
	v_pk_mul_f32 v[100:101], v[102:103], v[124:125]
	v_pk_mul_f32 v[98:99], v[104:105], v[98:99]
	v_pk_mul_f32 v[102:103], v[118:119], v[118:119]
	v_pk_mul_f32 v[104:105], v[120:121], v[120:121]
	v_pk_mul_f32 v[102:103], v[118:119], v[102:103]
	v_pk_mul_f32 v[104:105], v[120:121], v[104:105]
	v_pk_fma_f32 v[102:103], v[102:103], s[2:3], v[118:119] op_sel_hi:[1,0,1]
	v_pk_fma_f32 v[104:105], v[104:105], s[2:3], v[120:121] op_sel_hi:[1,0,1]
	v_pk_mul_f32 v[102:103], v[102:103], s[4:5] op_sel_hi:[1,0]
	v_pk_mul_f32 v[104:105], v[104:105], s[4:5] op_sel_hi:[1,0]
	v_min_f32_e32 v102, 0x41f00000, v102
	v_min_f32_e32 v104, 0x41f00000, v104
	v_exp_f32_e32 v123, v104
	v_min_f32_e32 v104, 0x41f00000, v105
	v_exp_f32_e32 v105, v102
	v_min_f32_e32 v102, 0x41f00000, v103
	v_exp_f32_e32 v122, v104
	v_exp_f32_e32 v104, v102
	v_pk_add_f32 v[102:103], v[122:123], 1.0 op_sel_hi:[1,0]
	v_pk_add_f32 v[104:105], v[104:105], 1.0 op_sel_hi:[1,0]
	v_mul_f32_e32 v122, v103, v102
	v_mul_f32_e32 v123, v105, v104
	s_nop 0
	v_mul_f32_e32 v124, v122, v123
	v_rcp_f32_e32 v125, v124
	s_nop 0
	v_mul_f32_e32 v124, v123, v125
	v_mul_f32_e32 v122, v122, v125
	v_pk_mul_f32 v[124:125], v[102:103], v[124:125] op_sel_hi:[1,0]
	v_pk_mul_f32 v[102:103], v[104:105], v[122:123] op_sel_hi:[1,0]
	v_pk_mul_f32 v[104:105], v[120:121], v[124:125]
	v_pk_mul_f32 v[102:103], v[118:119], v[102:103]
	v_cvt_pk_bf16_f32 v118, v100, v101
	v_cvt_pk_bf16_f32 v119, v98, v99
	v_cvt_pk_bf16_f32 v120, v104, v105
	s_nop 0
	v_cvt_pk_bf16_f32 v121, v102, v103
	global_store_dwordx4 v[116:117], v[118:121], off offset:256
	s_cbranch_vccnz .LBB0_596
; __device__ __forceinline__ unsigned cvt_pk_bf16(float lo, float hi) { unsigned r; asm volatile("v_cvt_pk_bf16_f32 %0, %1, %2" : "=v"(r) : "v"(lo), "v"(hi)); return r; }
;     __device__ __forceinline__ void operator()(const f32x4 (&acc)[2][2][4][2], const Unit& u, int wr, int wc, int fr, int fq) const {
;     ...
;                     s1 += ((v0[0] + v0[1]) + (v0[2] + v0[3])) + ((v1[0] + v1[1]) + (v1[2] + v1[3]));
;                     s2 += ((v0[0] * v0[0] + v0[1] * v0[1]) + (v0[2] * v0[2] + v0[3] * v0[3])) + ((v1[0] * v1[0] + v1[1] * v1[1]) + (v1[2] * v1[2] + v1[3] * v1[3]));
;                     u32x4 w; w.x = cvt_pk_bf16(v0[0], v0[1]); w.y = cvt_pk_bf16(v0[2], v0[3]); w.z = cvt_pk_bf16(v1[0], v1[1]); w.w = cvt_pk_bf16(v1[2], v1[3]);
;                     *(u32x4*)(rowp + bj * HALF) = w; }
;                 if (u.pn * BM >= stat_col0) {
;                     s1 += __shfl_xor(s1, 16); s1 += __shfl_xor(s1, 32); s2 += __shfl_xor(s2, 16); s2 += __shfl_xor(s2, 32);
;                     if (fq == 0) { float* sp = stats + (size_t)(row0 + ai * HALF + m * 16) * 32 + (((u.pn * BM - stat_col0) >> 8) * 4 + wc) * 2; sp[0] = s1; sp[1] = s2; } } }
	v_mul_f32_e32 v123, v107, v107
	v_add_f32_e32 v134, v106, v107
	v_and_b32_e32 v107, 64, v203
	v_mul_f32_e32 v121, v106, v106
	v_mul_f32_e32 v129, v110, v110
	v_pk_mul_f32 v[140:141], v[102:103], v[102:103]
	v_pk_mul_f32 v[142:143], v[104:105], v[104:105]
	v_add_f32_e32 v138, v110, v111
	v_xor_b32_e32 v106, 16, v203
	v_add_u32_e32 v110, 64, v107
	v_mul_f32_e32 v117, v108, v108
	v_mul_f32_e32 v119, v109, v109
	v_mov_b32_e32 v144, v142
	v_mov_b32_e32 v145, v141
	v_pk_mov_b32 v[140:141], v[142:143], v[140:141] op_sel:[1,0]
	v_cmp_lt_i32_e32 vcc, v106, v110
	v_mov_b32_e32 v116, v100
	v_mov_b32_e32 v118, v101
	v_mov_b32_e32 v120, v98
	v_mov_b32_e32 v122, v99
	v_mul_f32_e32 v125, v112, v112
	v_mul_f32_e32 v127, v113, v113
	v_mul_f32_e32 v131, v111, v111
	v_mul_f32_e32 v133, v100, v100
	v_mul_f32_e32 v135, v101, v101
	v_mul_f32_e32 v137, v98, v98
	v_mul_f32_e32 v139, v99, v99
	v_pk_add_f32 v[140:141], v[140:141], v[144:145]
	v_add_f32_e32 v132, v108, v109
	v_add_f32_e32 v136, v112, v113
	v_cndmask_b32_e32 v106, v203, v106, vcc
	v_pk_add_f32 v[100:101], v[116:117], v[118:119]
	v_pk_add_f32 v[98:99], v[120:121], v[122:123]
	v_mov_b32_e32 v124, v104
	v_mov_b32_e32 v126, v105
	v_mov_b32_e32 v128, v102
	v_mov_b32_e32 v130, v103
	v_pk_add_f32 v[140:141], v[140:141], v[140:141] op_sel_hi:[0,1]
	v_lshlrev_b32_e32 v111, 2, v106
	v_pk_add_f32 v[106:107], v[132:133], v[134:135]
	v_pk_add_f32 v[108:109], v[136:137], v[138:139]
	v_pk_add_f32 v[98:99], v[100:101], v[98:99]
	v_pk_add_f32 v[100:101], v[124:125], v[126:127]
	v_pk_add_f32 v[102:103], v[128:129], v[130:131]
	v_pk_add_f32 v[106:107], v[106:107], v[108:109]
	v_mov_b32_e32 v140, v1
	v_pk_add_f32 v[100:101], v[100:101], v[102:103]
	v_pk_add_f32 v[106:107], v[106:107], v[140:141]
	v_pk_add_f32 v[98:99], v[98:99], v[100:101]
	v_xor_b32_e32 v102, 32, v203
	v_pk_add_f32 v[98:99], v[98:99], v[106:107]
	ds_bpermute_b32 v100, v111, v98
	ds_bpermute_b32 v101, v111, v99
	v_cmp_lt_i32_e32 vcc, v102, v110
	s_waitcnt lgkmcnt(0)
	v_pk_add_f32 v[98:99], v[98:99], v[100:101]
	v_cndmask_b32_e32 v102, v203, v102, vcc
	v_lshlrev_b32_e32 v102, 2, v102
	ds_bpermute_b32 v100, v102, v98
	ds_bpermute_b32 v101, v102, v99
	s_and_saveexec_b64 s[2:3], s[36:37]
	s_cbranch_execz .LBB0_595
	s_add_i32 s4, s10, 0xfffffc00
	s_lshr_b32 s4, s4, 6
	v_readlane_b32 s8, v248, 10
	v_lshlrev_b64 v[102:103], 7, v[114:115]
	s_or_b32 s4, s4, s59
	v_readlane_b32 s9, v248, 11
	v_lshl_add_u64 v[102:103], s[86:87], 0, v[102:103]
	s_lshl_b32 s8, s4, 3
	s_mov_b32 s5, s9
	v_writelane_b32 v248, s4, 10
	v_lshl_add_u64 v[102:103], v[102:103], 0, s[8:9]
	s_waitcnt lgkmcnt(0)
	v_pk_add_f32 v[98:99], v[98:99], v[100:101]
	v_writelane_b32 v248, s5, 11
	global_store_dwordx2 v[102:103], v[98:99], off

; __device__ __forceinline__ unsigned cvt_pk_bf16(float lo, float hi) { unsigned r; asm volatile("v_cvt_pk_bf16_f32 %0, %1, %2" : "=v"(r) : "v"(lo), "v"(hi)); return r; }
; __device__ __forceinline__ f32x4 inv4_1p_exp2(f32x4 t) {
;     f32x4 d;
; #pragma unroll
;     for (int i = 0; i < 4; ++i) d[i] = 1.0f + __builtin_amdgcn_exp2f(fminf(t[i], 30.0f));
;     const float p01 = d[0] * d[1], p23 = d[2] * d[3], r = __builtin_amdgcn_rcpf(p01 * p23), r01 = r * p23, r23 = r * p01;
;     return (f32x4){r01 * d[1], r01 * d[0], r23 * d[3], r23 * d[2]};
; }
; __device__ __forceinline__ f32x4 gelu_tanh4(f32x4 x) { const f32x4 u = (x + (x * x * x) * 0.044715f) * (-2.885390081777927f * 0.7978845608028654f); return x * inv4_1p_exp2(u); }
;     __device__ __forceinline__ void operator()(const f32x4 (&acc)[2][2][4][2], const Unit& u, int wr, int wc, int fr, int fq) const {
;     ...
;             for (int m = 0; m < 4; ++m) { bf16_t* rowp = O + (size_t)(row0 + ai * HALF + m * 16) * ldc + col0;
;                 float s1 = 0.f, s2 = 0.f;
; #pragma unroll
;                 for (int bj = 0; bj < 2; ++bj) { f32x4 v0 = acc[ai][bj][m][0] + bv[bj][0], v1 = acc[ai][bj][m][1] + bv[bj][1];
;                     v0 = gelu_tanh4(v0); v1 = gelu_tanh4(v1);
;                     s1 += ((v0[0] + v0[1]) + (v0[2] + v0[3])) + ((v1[0] + v1[1]) + (v1[2] + v1[3]));
;                     s2 += ((v0[0] * v0[0] + v0[1] * v0[1]) + (v0[2] * v0[2] + v0[3] * v0[3])) + ((v1[0] * v1[0] + v1[1] * v1[1]) + (v1[2] * v1[2] + v1[3] * v1[3]));
;                     u32x4 w; w.x = cvt_pk_bf16(v0[0], v0[1]); w.y = cvt_pk_bf16(v0[2], v0[3]); w.z = cvt_pk_bf16(v1[0], v1[1]); w.w = cvt_pk_bf16(v1[2], v1[3]);
;                     *(u32x4*)(rowp + bj * HALF) = w; }
.LBB0_596:
	v_pk_add_f32 v[96:97], v[96:97], v[48:49]
	v_pk_add_f32 v[94:95], v[94:95], v[46:47]
	v_pk_add_f32 v[102:103], v[92:93], v[44:45]
	v_pk_add_f32 v[104:105], v[90:91], v[42:43]
	v_pk_mul_f32 v[90:91], v[96:97], v[96:97]
	v_pk_mul_f32 v[92:93], v[94:95], v[94:95]
	v_pk_mul_f32 v[90:91], v[96:97], v[90:91]
	v_pk_mul_f32 v[92:93], v[94:95], v[92:93]
	s_mov_b32 s2, 0x3d372713
	v_pk_fma_f32 v[90:91], v[90:91], s[2:3], v[96:97] op_sel_hi:[1,0,1]
	v_pk_fma_f32 v[92:93], v[92:93], s[2:3], v[94:95] op_sel_hi:[1,0,1]
	s_mov_b32 s4, 0xc0135761
	v_pk_mul_f32 v[90:91], v[90:91], s[4:5] op_sel_hi:[1,0]
	v_pk_mul_f32 v[92:93], v[92:93], s[4:5] op_sel_hi:[1,0]
	v_min_f32_e32 v90, 0x41f00000, v90
	v_min_f32_e32 v92, 0x41f00000, v92
	v_exp_f32_e32 v107, v92
	v_min_f32_e32 v92, 0x41f00000, v93
	v_exp_f32_e32 v93, v90
	v_min_f32_e32 v90, 0x41f00000, v91
	v_exp_f32_e32 v106, v92
	v_exp_f32_e32 v92, v90
	v_or_b32_e32 v98, 48, v168
	v_ashrrev_i32_e32 v99, 31, v98
	v_pk_add_f32 v[90:91], v[106:107], 1.0 op_sel_hi:[1,0]
	v_pk_add_f32 v[92:93], v[92:93], 1.0 op_sel_hi:[1,0]
	v_mul_f32_e32 v106, v91, v90
	v_mul_f32_e32 v107, v93, v92
	s_waitcnt lgkmcnt(0)
	v_lshlrev_b64 v[100:101], 12, v[98:99]
	v_mul_f32_e32 v108, v106, v107
	v_rcp_f32_e32 v109, v108
	v_lshl_add_u64 v[100:101], s[84:85], 0, v[100:101]
	v_lshl_add_u64 v[100:101], v[166:167], 1, v[100:101]
	v_pk_add_f32 v[88:89], v[88:89], v[40:41]
	v_mul_f32_e32 v108, v107, v109
	v_mul_f32_e32 v106, v106, v109
	v_pk_mul_f32 v[108:109], v[90:91], v[108:109] op_sel_hi:[1,0]
	v_pk_mul_f32 v[90:91], v[92:93], v[106:107] op_sel_hi:[1,0]
	v_pk_mul_f32 v[92:93], v[94:95], v[108:109]
	v_pk_mul_f32 v[90:91], v[96:97], v[90:91]
	v_pk_mul_f32 v[94:95], v[102:103], v[102:103]
	v_pk_mul_f32 v[96:97], v[104:105], v[104:105]
	v_pk_mul_f32 v[94:95], v[102:103], v[94:95]
	v_pk_mul_f32 v[96:97], v[104:105], v[96:97]
	v_pk_fma_f32 v[94:95], v[94:95], s[2:3], v[102:103] op_sel_hi:[1,0,1]
	v_pk_fma_f32 v[96:97], v[96:97], s[2:3], v[104:105] op_sel_hi:[1,0,1]
	v_pk_mul_f32 v[94:95], v[94:95], s[4:5] op_sel_hi:[1,0]
	v_pk_mul_f32 v[96:97], v[96:97], s[4:5] op_sel_hi:[1,0]
	v_min_f32_e32 v94, 0x41f00000, v94
	v_min_f32_e32 v96, 0x41f00000, v96
	v_exp_f32_e32 v107, v96
	v_min_f32_e32 v96, 0x41f00000, v97
	v_exp_f32_e32 v97, v94
	v_min_f32_e32 v94, 0x41f00000, v95
	v_exp_f32_e32 v106, v96
	v_exp_f32_e32 v96, v94
	v_pk_add_f32 v[86:87], v[86:87], v[38:39]
	s_and_b64 vcc, exec, s[40:41]
	v_pk_add_f32 v[94:95], v[106:107], 1.0 op_sel_hi:[1,0]
	v_pk_add_f32 v[96:97], v[96:97], 1.0 op_sel_hi:[1,0]
	v_mul_f32_e32 v106, v95, v94
	v_mul_f32_e32 v107, v97, v96
	s_nop 0
	v_mul_f32_e32 v108, v106, v107
	v_rcp_f32_e32 v109, v108
	s_nop 0
	v_mul_f32_e32 v108, v107, v109
	v_mul_f32_e32 v106, v106, v109
	v_pk_mul_f32 v[108:109], v[94:95], v[108:109] op_sel_hi:[1,0]
	v_pk_mul_f32 v[94:95], v[96:97], v[106:107] op_sel_hi:[1,0]
	v_pk_mul_f32 v[96:97], v[104:105], v[108:109]
	v_pk_mul_f32 v[94:95], v[102:103], v[94:95]
	v_cvt_pk_bf16_f32 v102, v92, v93
	v_cvt_pk_bf16_f32 v103, v90, v91
	v_cvt_pk_bf16_f32 v104, v96, v97
	s_nop 0
	v_cvt_pk_bf16_f32 v105, v94, v95
	global_store_dwordx4 v[100:101], v[102:105], off
	s_nop 1
	v_pk_add_f32 v[102:103], v[84:85], v[36:37]
	v_pk_add_f32 v[104:105], v[82:83], v[34:35]
	v_pk_mul_f32 v[82:83], v[88:89], v[88:89]
	v_pk_mul_f32 v[84:85], v[86:87], v[86:87]
	v_pk_mul_f32 v[82:83], v[88:89], v[82:83]
	v_pk_mul_f32 v[84:85], v[86:87], v[84:85]
	v_pk_fma_f32 v[82:83], v[82:83], s[2:3], v[88:89] op_sel_hi:[1,0,1]
	v_pk_fma_f32 v[84:85], v[84:85], s[2:3], v[86:87] op_sel_hi:[1,0,1]
	v_pk_mul_f32 v[82:83], v[82:83], s[4:5] op_sel_hi:[1,0]
	v_pk_mul_f32 v[84:85], v[84:85], s[4:5] op_sel_hi:[1,0]
	v_min_f32_e32 v82, 0x41f00000, v82
	v_min_f32_e32 v84, 0x41f00000, v84
	v_exp_f32_e32 v107, v84
	v_min_f32_e32 v84, 0x41f00000, v85
	v_exp_f32_e32 v85, v82
	v_min_f32_e32 v82, 0x41f00000, v83
	v_exp_f32_e32 v106, v84
	v_exp_f32_e32 v84, v82
	v_pk_add_f32 v[82:83], v[106:107], 1.0 op_sel_hi:[1,0]
	v_pk_add_f32 v[84:85], v[84:85], 1.0 op_sel_hi:[1,0]
	v_mul_f32_e32 v106, v83, v82
	v_mul_f32_e32 v107, v85, v84
	s_nop 0
	v_mul_f32_e32 v108, v106, v107
	v_rcp_f32_e32 v109, v108
	s_nop 0
	v_mul_f32_e32 v108, v107, v109
	v_mul_f32_e32 v106, v106, v109
	v_pk_mul_f32 v[108:109], v[82:83], v[108:109] op_sel_hi:[1,0]
	v_pk_mul_f32 v[82:83], v[84:85], v[106:107] op_sel_hi:[1,0]
	v_pk_mul_f32 v[84:85], v[86:87], v[108:109]
	v_pk_mul_f32 v[82:83], v[88:89], v[82:83]
	v_pk_mul_f32 v[86:87], v[102:103], v[102:103]
	v_pk_mul_f32 v[88:89], v[104:105], v[104:105]
	v_pk_mul_f32 v[86:87], v[102:103], v[86:87]
	v_pk_mul_f32 v[88:89], v[104:105], v[88:89]
	v_pk_fma_f32 v[86:87], v[86:87], s[2:3], v[102:103] op_sel_hi:[1,0,1]
	v_pk_fma_f32 v[88:89], v[88:89], s[2:3], v[104:105] op_sel_hi:[1,0,1]
	v_pk_mul_f32 v[86:87], v[86:87], s[4:5] op_sel_hi:[1,0]
	v_pk_mul_f32 v[88:89], v[88:89], s[4:5] op_sel_hi:[1,0]
	v_min_f32_e32 v86, 0x41f00000, v86
	v_min_f32_e32 v88, 0x41f00000, v88
	v_exp_f32_e32 v107, v88
	v_min_f32_e32 v88, 0x41f00000, v89
	v_exp_f32_e32 v89, v86
	v_min_f32_e32 v86, 0x41f00000, v87
	v_exp_f32_e32 v106, v88
	v_exp_f32_e32 v88, v86
	v_pk_add_f32 v[86:87], v[106:107], 1.0 op_sel_hi:[1,0]
	v_pk_add_f32 v[88:89], v[88:89], 1.0 op_sel_hi:[1,0]
	v_mul_f32_e32 v106, v87, v86
	v_mul_f32_e32 v107, v89, v88
	s_nop 0
	v_mul_f32_e32 v108, v106, v107
	v_rcp_f32_e32 v109, v108
	s_nop 0
	v_mul_f32_e32 v108, v107, v109
	v_mul_f32_e32 v106, v106, v109
	v_pk_mul_f32 v[108:109], v[86:87], v[108:109] op_sel_hi:[1,0]
	v_pk_mul_f32 v[86:87], v[88:89], v[106:107] op_sel_hi:[1,0]
	v_pk_mul_f32 v[88:89], v[104:105], v[108:109]
	v_pk_mul_f32 v[86:87], v[102:103], v[86:87]
	v_cvt_pk_bf16_f32 v102, v84, v85
	v_cvt_pk_bf16_f32 v103, v82, v83
	v_cvt_pk_bf16_f32 v104, v88, v89
	s_nop 0
	v_cvt_pk_bf16_f32 v105, v86, v87
	global_store_dwordx4 v[100:101], v[102:105], off offset:256
	s_cbranch_vccnz .LBB0_600
; __device__ __forceinline__ unsigned cvt_pk_bf16(float lo, float hi) { unsigned r; asm volatile("v_cvt_pk_bf16_f32 %0, %1, %2" : "=v"(r) : "v"(lo), "v"(hi)); return r; }
;     __device__ __forceinline__ void operator()(const f32x4 (&acc)[2][2][4][2], const Unit& u, int wr, int wc, int fr, int fq) const {
;     ...
;                     s1 += ((v0[0] + v0[1]) + (v0[2] + v0[3])) + ((v1[0] + v1[1]) + (v1[2] + v1[3]));
;                     s2 += ((v0[0] * v0[0] + v0[1] * v0[1]) + (v0[2] * v0[2] + v0[3] * v0[3])) + ((v1[0] * v1[0] + v1[1] * v1[1]) + (v1[2] * v1[2] + v1[3] * v1[3]));
;                     u32x4 w; w.x = cvt_pk_bf16(v0[0], v0[1]); w.y = cvt_pk_bf16(v0[2], v0[3]); w.z = cvt_pk_bf16(v1[0], v1[1]); w.w = cvt_pk_bf16(v1[2], v1[3]);
;                     *(u32x4*)(rowp + bj * HALF) = w; }
;                 if (u.pn * BM >= stat_col0) {
;                     s1 += __shfl_xor(s1, 16); s1 += __shfl_xor(s1, 32); s2 += __shfl_xor(s2, 16); s2 += __shfl_xor(s2, 32);
;                     if (fq == 0) { float* sp = stats + (size_t)(row0 + ai * HALF + m * 16) * 32 + (((u.pn * BM - stat_col0) >> 8) * 4 + wc) * 2; sp[0] = s1; sp[1] = s2; } } }
	v_mul_f32_e32 v107, v91, v91
	v_add_f32_e32 v118, v90, v91
	v_and_b32_e32 v91, 64, v203
	v_mul_f32_e32 v105, v90, v90
	v_mul_f32_e32 v113, v94, v94
	v_pk_mul_f32 v[124:125], v[86:87], v[86:87]
	v_pk_mul_f32 v[126:127], v[88:89], v[88:89]
	v_add_f32_e32 v122, v94, v95
	v_xor_b32_e32 v90, 16, v203
	v_add_u32_e32 v94, 64, v91
	v_mul_f32_e32 v101, v92, v92
	v_mul_f32_e32 v103, v93, v93
	v_mov_b32_e32 v128, v126
	v_mov_b32_e32 v129, v125
	v_pk_mov_b32 v[124:125], v[126:127], v[124:125] op_sel:[1,0]
	v_cmp_lt_i32_e32 vcc, v90, v94
	v_mov_b32_e32 v100, v84
	v_mov_b32_e32 v102, v85
	v_mov_b32_e32 v104, v82
	v_mov_b32_e32 v106, v83
	v_mul_f32_e32 v109, v96, v96
	v_mul_f32_e32 v111, v97, v97
	v_mul_f32_e32 v115, v95, v95
	v_mul_f32_e32 v117, v84, v84
	v_mul_f32_e32 v119, v85, v85
	v_mul_f32_e32 v121, v82, v82
	v_mul_f32_e32 v123, v83, v83
	v_pk_add_f32 v[124:125], v[124:125], v[128:129]
	v_add_f32_e32 v116, v92, v93
	v_add_f32_e32 v120, v96, v97
	v_cndmask_b32_e32 v90, v203, v90, vcc
	v_pk_add_f32 v[84:85], v[100:101], v[102:103]
	v_pk_add_f32 v[82:83], v[104:105], v[106:107]
	v_mov_b32_e32 v108, v88
	v_mov_b32_e32 v110, v89
	v_mov_b32_e32 v112, v86
	v_mov_b32_e32 v114, v87
	v_pk_add_f32 v[124:125], v[124:125], v[124:125] op_sel_hi:[0,1]
	v_lshlrev_b32_e32 v95, 2, v90
	v_pk_add_f32 v[90:91], v[116:117], v[118:119]
	v_pk_add_f32 v[92:93], v[120:121], v[122:123]
	v_pk_add_f32 v[82:83], v[84:85], v[82:83]
	v_pk_add_f32 v[84:85], v[108:109], v[110:111]
	v_pk_add_f32 v[86:87], v[112:113], v[114:115]
	v_pk_add_f32 v[90:91], v[90:91], v[92:93]
	v_mov_b32_e32 v124, v1
	v_pk_add_f32 v[84:85], v[84:85], v[86:87]
	v_pk_add_f32 v[90:91], v[90:91], v[124:125]
	v_pk_add_f32 v[82:83], v[82:83], v[84:85]
	v_xor_b32_e32 v86, 32, v203
	v_pk_add_f32 v[82:83], v[82:83], v[90:91]
	ds_bpermute_b32 v84, v95, v82
	ds_bpermute_b32 v85, v95, v83
	v_cmp_lt_i32_e32 vcc, v86, v94
	s_waitcnt lgkmcnt(0)
	v_pk_add_f32 v[82:83], v[82:83], v[84:85]
	v_cndmask_b32_e32 v86, v203, v86, vcc
	v_lshlrev_b32_e32 v86, 2, v86
	ds_bpermute_b32 v84, v86, v82
	ds_bpermute_b32 v85, v86, v83
	s_and_saveexec_b64 s[2:3], s[36:37]
	s_cbranch_execz .LBB0_599
	s_add_i32 s4, s10, 0xfffffc00
	s_lshr_b32 s4, s4, 6
	v_readlane_b32 s8, v248, 10
	v_lshlrev_b64 v[86:87], 7, v[98:99]
	s_or_b32 s4, s4, s59
	v_readlane_b32 s9, v248, 11
	v_lshl_add_u64 v[86:87], s[86:87], 0, v[86:87]
	s_lshl_b32 s8, s4, 3
	s_mov_b32 s5, s9
	v_writelane_b32 v248, s4, 10
	v_lshl_add_u64 v[86:87], v[86:87], 0, s[8:9]
	s_waitcnt lgkmcnt(0)
	v_pk_add_f32 v[82:83], v[82:83], v[84:85]
	v_writelane_b32 v248, s5, 11
	global_store_dwordx2 v[86:87], v[82:83], off

; __device__ __forceinline__ unsigned cvt_pk_bf16(float lo, float hi) { unsigned r; asm volatile("v_cvt_pk_bf16_f32 %0, %1, %2" : "=v"(r) : "v"(lo), "v"(hi)); return r; }
; __device__ __forceinline__ f32x4 inv4_1p_exp2(f32x4 t) {
;     f32x4 d;
; #pragma unroll
;     for (int i = 0; i < 4; ++i) d[i] = 1.0f + __builtin_amdgcn_exp2f(fminf(t[i], 30.0f));
;     const float p01 = d[0] * d[1], p23 = d[2] * d[3], r = __builtin_amdgcn_rcpf(p01 * p23), r01 = r * p23, r23 = r * p01;
;     return (f32x4){r01 * d[1], r01 * d[0], r23 * d[3], r23 * d[2]};
; }
; __device__ __forceinline__ f32x4 gelu_tanh4(f32x4 x) { const f32x4 u = (x + (x * x * x) * 0.044715f) * (-2.885390081777927f * 0.7978845608028654f); return x * inv4_1p_exp2(u); }
;     __device__ __forceinline__ void operator()(const f32x4 (&acc)[2][2][4][2], const Unit& u, int wr, int wc, int fr, int fq) const {
;     ...
;             for (int m = 0; m < 4; ++m) { bf16_t* rowp = O + (size_t)(row0 + ai * HALF + m * 16) * ldc + col0;
;                 float s1 = 0.f, s2 = 0.f;
; #pragma unroll
;                 for (int bj = 0; bj < 2; ++bj) { f32x4 v0 = acc[ai][bj][m][0] + bv[bj][0], v1 = acc[ai][bj][m][1] + bv[bj][1];
;                     v0 = gelu_tanh4(v0); v1 = gelu_tanh4(v1);
;                     s1 += ((v0[0] + v0[1]) + (v0[2] + v0[3])) + ((v1[0] + v1[1]) + (v1[2] + v1[3]));
;                     s2 += ((v0[0] * v0[0] + v0[1] * v0[1]) + (v0[2] * v0[2] + v0[3] * v0[3])) + ((v1[0] * v1[0] + v1[1] * v1[1]) + (v1[2] * v1[2] + v1[3] * v1[3]));
;                     u32x4 w; w.x = cvt_pk_bf16(v0[0], v0[1]); w.y = cvt_pk_bf16(v0[2], v0[3]); w.z = cvt_pk_bf16(v1[0], v1[1]); w.w = cvt_pk_bf16(v1[2], v1[3]);
;                     *(u32x4*)(rowp + bj * HALF) = w; }
.LBB0_600:
	v_pk_add_f32 v[80:81], v[80:81], v[48:49]
	v_pk_add_f32 v[78:79], v[78:79], v[46:47]
	v_pk_add_f32 v[86:87], v[76:77], v[44:45]
	v_pk_add_f32 v[88:89], v[74:75], v[42:43]
	v_pk_mul_f32 v[74:75], v[80:81], v[80:81]
	v_pk_mul_f32 v[76:77], v[78:79], v[78:79]
	v_pk_mul_f32 v[74:75], v[80:81], v[74:75]
	v_pk_mul_f32 v[76:77], v[78:79], v[76:77]
	s_mov_b32 s2, 0x3d372713
	v_pk_fma_f32 v[74:75], v[74:75], s[2:3], v[80:81] op_sel_hi:[1,0,1]
	v_pk_fma_f32 v[76:77], v[76:77], s[2:3], v[78:79] op_sel_hi:[1,0,1]
	s_mov_b32 s4, 0xc0135761
	v_pk_mul_f32 v[74:75], v[74:75], s[4:5] op_sel_hi:[1,0]
	v_pk_mul_f32 v[76:77], v[76:77], s[4:5] op_sel_hi:[1,0]
	v_min_f32_e32 v74, 0x41f00000, v74
	v_min_f32_e32 v76, 0x41f00000, v76
	v_exp_f32_e32 v91, v76
	v_min_f32_e32 v76, 0x41f00000, v77
	v_exp_f32_e32 v77, v74
	v_min_f32_e32 v74, 0x41f00000, v75
	v_exp_f32_e32 v90, v76
	v_exp_f32_e32 v76, v74
	v_add_u32_e32 v82, 0x80, v168
	v_ashrrev_i32_e32 v83, 31, v82
	v_pk_add_f32 v[74:75], v[90:91], 1.0 op_sel_hi:[1,0]
	v_pk_add_f32 v[76:77], v[76:77], 1.0 op_sel_hi:[1,0]
	v_mul_f32_e32 v90, v75, v74
	v_mul_f32_e32 v91, v77, v76
	s_waitcnt lgkmcnt(0)
	v_lshlrev_b64 v[84:85], 12, v[82:83]
	v_mul_f32_e32 v92, v90, v91
	v_rcp_f32_e32 v93, v92
	v_lshl_add_u64 v[84:85], s[84:85], 0, v[84:85]
	v_lshl_add_u64 v[84:85], v[166:167], 1, v[84:85]
	v_pk_add_f32 v[72:73], v[72:73], v[40:41]
	v_mul_f32_e32 v92, v91, v93
	v_mul_f32_e32 v90, v90, v93
	v_pk_mul_f32 v[92:93], v[74:75], v[92:93] op_sel_hi:[1,0]
	v_pk_mul_f32 v[74:75], v[76:77], v[90:91] op_sel_hi:[1,0]
	v_pk_mul_f32 v[76:77], v[78:79], v[92:93]
	v_pk_mul_f32 v[74:75], v[80:81], v[74:75]
	v_pk_mul_f32 v[78:79], v[86:87], v[86:87]
	v_pk_mul_f32 v[80:81], v[88:89], v[88:89]
	v_pk_mul_f32 v[78:79], v[86:87], v[78:79]
	v_pk_mul_f32 v[80:81], v[88:89], v[80:81]
	v_pk_fma_f32 v[78:79], v[78:79], s[2:3], v[86:87] op_sel_hi:[1,0,1]
	v_pk_fma_f32 v[80:81], v[80:81], s[2:3], v[88:89] op_sel_hi:[1,0,1]
	v_pk_mul_f32 v[78:79], v[78:79], s[4:5] op_sel_hi:[1,0]
	v_pk_mul_f32 v[80:81], v[80:81], s[4:5] op_sel_hi:[1,0]
	v_min_f32_e32 v78, 0x41f00000, v78
	v_min_f32_e32 v80, 0x41f00000, v80
	v_exp_f32_e32 v91, v80
	v_min_f32_e32 v80, 0x41f00000, v81
	v_exp_f32_e32 v81, v78
	v_min_f32_e32 v78, 0x41f00000, v79
	v_exp_f32_e32 v90, v80
	v_exp_f32_e32 v80, v78
	v_pk_add_f32 v[70:71], v[70:71], v[38:39]
	s_and_b64 vcc, exec, s[40:41]
	v_pk_add_f32 v[78:79], v[90:91], 1.0 op_sel_hi:[1,0]
	v_pk_add_f32 v[80:81], v[80:81], 1.0 op_sel_hi:[1,0]
	v_mul_f32_e32 v90, v79, v78
	v_mul_f32_e32 v91, v81, v80
	s_nop 0
	v_mul_f32_e32 v92, v90, v91
	v_rcp_f32_e32 v93, v92
	s_nop 0
	v_mul_f32_e32 v92, v91, v93
	v_mul_f32_e32 v90, v90, v93
	v_pk_mul_f32 v[92:93], v[78:79], v[92:93] op_sel_hi:[1,0]
	v_pk_mul_f32 v[78:79], v[80:81], v[90:91] op_sel_hi:[1,0]
	v_pk_mul_f32 v[80:81], v[88:89], v[92:93]
	v_pk_mul_f32 v[78:79], v[86:87], v[78:79]
	v_cvt_pk_bf16_f32 v86, v76, v77
	v_cvt_pk_bf16_f32 v87, v74, v75
	v_cvt_pk_bf16_f32 v88, v80, v81
	s_nop 0
	v_cvt_pk_bf16_f32 v89, v78, v79
	global_store_dwordx4 v[84:85], v[86:89], off
	s_nop 1
	v_pk_add_f32 v[86:87], v[68:69], v[36:37]
	v_pk_add_f32 v[88:89], v[66:67], v[34:35]
	v_pk_mul_f32 v[66:67], v[72:73], v[72:73]
	v_pk_mul_f32 v[68:69], v[70:71], v[70:71]
	v_pk_mul_f32 v[66:67], v[72:73], v[66:67]
	v_pk_mul_f32 v[68:69], v[70:71], v[68:69]
	v_pk_fma_f32 v[66:67], v[66:67], s[2:3], v[72:73] op_sel_hi:[1,0,1]
	v_pk_fma_f32 v[68:69], v[68:69], s[2:3], v[70:71] op_sel_hi:[1,0,1]
	v_pk_mul_f32 v[66:67], v[66:67], s[4:5] op_sel_hi:[1,0]
	v_pk_mul_f32 v[68:69], v[68:69], s[4:5] op_sel_hi:[1,0]
	v_min_f32_e32 v66, 0x41f00000, v66
	v_min_f32_e32 v68, 0x41f00000, v68
	v_exp_f32_e32 v91, v68
	v_min_f32_e32 v68, 0x41f00000, v69
	v_exp_f32_e32 v69, v66
	v_min_f32_e32 v66, 0x41f00000, v67
	v_exp_f32_e32 v90, v68
	v_exp_f32_e32 v68, v66
	v_pk_add_f32 v[66:67], v[90:91], 1.0 op_sel_hi:[1,0]
	v_pk_add_f32 v[68:69], v[68:69], 1.0 op_sel_hi:[1,0]
	v_mul_f32_e32 v90, v67, v66
	v_mul_f32_e32 v91, v69, v68
	s_nop 0
	v_mul_f32_e32 v92, v90, v91
	v_rcp_f32_e32 v93, v92
	s_nop 0
	v_mul_f32_e32 v92, v91, v93
	v_mul_f32_e32 v90, v90, v93
	v_pk_mul_f32 v[92:93], v[66:67], v[92:93] op_sel_hi:[1,0]
	v_pk_mul_f32 v[66:67], v[68:69], v[90:91] op_sel_hi:[1,0]
	v_pk_mul_f32 v[68:69], v[70:71], v[92:93]
	v_pk_mul_f32 v[66:67], v[72:73], v[66:67]
	v_pk_mul_f32 v[70:71], v[86:87], v[86:87]
	v_pk_mul_f32 v[72:73], v[88:89], v[88:89]
	v_pk_mul_f32 v[70:71], v[86:87], v[70:71]
	v_pk_mul_f32 v[72:73], v[88:89], v[72:73]
	v_pk_fma_f32 v[70:71], v[70:71], s[2:3], v[86:87] op_sel_hi:[1,0,1]
	v_pk_fma_f32 v[72:73], v[72:73], s[2:3], v[88:89] op_sel_hi:[1,0,1]
	v_pk_mul_f32 v[70:71], v[70:71], s[4:5] op_sel_hi:[1,0]
	v_pk_mul_f32 v[72:73], v[72:73], s[4:5] op_sel_hi:[1,0]
	v_min_f32_e32 v70, 0x41f00000, v70
	v_min_f32_e32 v72, 0x41f00000, v72
	v_exp_f32_e32 v91, v72
	v_min_f32_e32 v72, 0x41f00000, v73
	v_exp_f32_e32 v73, v70
	v_min_f32_e32 v70, 0x41f00000, v71
	v_exp_f32_e32 v90, v72
	v_exp_f32_e32 v72, v70
	v_pk_add_f32 v[70:71], v[90:91], 1.0 op_sel_hi:[1,0]
	v_pk_add_f32 v[72:73], v[72:73], 1.0 op_sel_hi:[1,0]
	v_mul_f32_e32 v90, v71, v70
	v_mul_f32_e32 v91, v73, v72
	s_nop 0
	v_mul_f32_e32 v92, v90, v91
	v_rcp_f32_e32 v93, v92
	s_nop 0
	v_mul_f32_e32 v92, v91, v93
	v_mul_f32_e32 v90, v90, v93
	v_pk_mul_f32 v[92:93], v[70:71], v[92:93] op_sel_hi:[1,0]
	v_pk_mul_f32 v[70:71], v[72:73], v[90:91] op_sel_hi:[1,0]
	v_pk_mul_f32 v[72:73], v[88:89], v[92:93]
	v_pk_mul_f32 v[70:71], v[86:87], v[70:71]
	v_cvt_pk_bf16_f32 v86, v68, v69
	v_cvt_pk_bf16_f32 v87, v66, v67
	v_cvt_pk_bf16_f32 v88, v72, v73
	s_nop 0
	v_cvt_pk_bf16_f32 v89, v70, v71
	global_store_dwordx4 v[84:85], v[86:89], off offset:256
	s_cbranch_vccnz .LBB0_604
; __device__ __forceinline__ unsigned cvt_pk_bf16(float lo, float hi) { unsigned r; asm volatile("v_cvt_pk_bf16_f32 %0, %1, %2" : "=v"(r) : "v"(lo), "v"(hi)); return r; }
;     __device__ __forceinline__ void operator()(const f32x4 (&acc)[2][2][4][2], const Unit& u, int wr, int wc, int fr, int fq) const {
;     ...
;                     s1 += ((v0[0] + v0[1]) + (v0[2] + v0[3])) + ((v1[0] + v1[1]) + (v1[2] + v1[3]));
;                     s2 += ((v0[0] * v0[0] + v0[1] * v0[1]) + (v0[2] * v0[2] + v0[3] * v0[3])) + ((v1[0] * v1[0] + v1[1] * v1[1]) + (v1[2] * v1[2] + v1[3] * v1[3]));
;                     u32x4 w; w.x = cvt_pk_bf16(v0[0], v0[1]); w.y = cvt_pk_bf16(v0[2], v0[3]); w.z = cvt_pk_bf16(v1[0], v1[1]); w.w = cvt_pk_bf16(v1[2], v1[3]);
;                     *(u32x4*)(rowp + bj * HALF) = w; }
;                 if (u.pn * BM >= stat_col0) {
;                     s1 += __shfl_xor(s1, 16); s1 += __shfl_xor(s1, 32); s2 += __shfl_xor(s2, 16); s2 += __shfl_xor(s2, 32);
;                     if (fq == 0) { float* sp = stats + (size_t)(row0 + ai * HALF + m * 16) * 32 + (((u.pn * BM - stat_col0) >> 8) * 4 + wc) * 2; sp[0] = s1; sp[1] = s2; } } }
	v_mul_f32_e32 v91, v75, v75
	v_add_f32_e32 v102, v74, v75
	v_and_b32_e32 v75, 64, v203
	v_mul_f32_e32 v89, v74, v74
	v_mul_f32_e32 v97, v78, v78
	v_pk_mul_f32 v[108:109], v[70:71], v[70:71]
	v_pk_mul_f32 v[110:111], v[72:73], v[72:73]
	v_add_f32_e32 v106, v78, v79
	v_xor_b32_e32 v74, 16, v203
	v_add_u32_e32 v78, 64, v75
	v_mul_f32_e32 v85, v76, v76
	v_mul_f32_e32 v87, v77, v77
	v_mov_b32_e32 v112, v110
	v_mov_b32_e32 v113, v109
	v_pk_mov_b32 v[108:109], v[110:111], v[108:109] op_sel:[1,0]
	v_cmp_lt_i32_e32 vcc, v74, v78
	v_mov_b32_e32 v84, v68
	v_mov_b32_e32 v86, v69
	v_mov_b32_e32 v88, v66
	v_mov_b32_e32 v90, v67
	v_mul_f32_e32 v93, v80, v80
	v_mul_f32_e32 v95, v81, v81
	v_mul_f32_e32 v99, v79, v79
	v_mul_f32_e32 v101, v68, v68
	v_mul_f32_e32 v103, v69, v69
	v_mul_f32_e32 v105, v66, v66
	v_mul_f32_e32 v107, v67, v67
	v_pk_add_f32 v[108:109], v[108:109], v[112:113]
	v_add_f32_e32 v100, v76, v77
	v_add_f32_e32 v104, v80, v81
	v_cndmask_b32_e32 v74, v203, v74, vcc
	v_pk_add_f32 v[68:69], v[84:85], v[86:87]
	v_pk_add_f32 v[66:67], v[88:89], v[90:91]
	v_mov_b32_e32 v92, v72
	v_mov_b32_e32 v94, v73
	v_mov_b32_e32 v96, v70
	v_mov_b32_e32 v98, v71
	v_pk_add_f32 v[108:109], v[108:109], v[108:109] op_sel_hi:[0,1]
	v_lshlrev_b32_e32 v79, 2, v74
	v_pk_add_f32 v[74:75], v[100:101], v[102:103]
	v_pk_add_f32 v[76:77], v[104:105], v[106:107]
	v_pk_add_f32 v[66:67], v[68:69], v[66:67]
	v_pk_add_f32 v[68:69], v[92:93], v[94:95]
	v_pk_add_f32 v[70:71], v[96:97], v[98:99]
	v_pk_add_f32 v[74:75], v[74:75], v[76:77]
	v_mov_b32_e32 v108, v1
	v_pk_add_f32 v[68:69], v[68:69], v[70:71]
	v_pk_add_f32 v[74:75], v[74:75], v[108:109]
	v_pk_add_f32 v[66:67], v[66:67], v[68:69]
	v_xor_b32_e32 v70, 32, v203
	v_pk_add_f32 v[66:67], v[66:67], v[74:75]
	ds_bpermute_b32 v68, v79, v66
	ds_bpermute_b32 v69, v79, v67
	v_cmp_lt_i32_e32 vcc, v70, v78
	s_waitcnt lgkmcnt(0)
	v_pk_add_f32 v[66:67], v[66:67], v[68:69]
	v_cndmask_b32_e32 v70, v203, v70, vcc
	v_lshlrev_b32_e32 v70, 2, v70
	ds_bpermute_b32 v68, v70, v66
	ds_bpermute_b32 v69, v70, v67
	s_and_saveexec_b64 s[2:3], s[36:37]
	s_cbranch_execz .LBB0_603
	s_add_i32 s4, s10, 0xfffffc00
	s_lshr_b32 s4, s4, 6
	v_readlane_b32 s8, v248, 10
	v_lshlrev_b64 v[70:71], 7, v[82:83]
	s_or_b32 s4, s4, s59
	v_readlane_b32 s9, v248, 11
	v_lshl_add_u64 v[70:71], s[86:87], 0, v[70:71]
	s_lshl_b32 s8, s4, 3
	s_mov_b32 s5, s9
	v_writelane_b32 v248, s4, 10
	v_lshl_add_u64 v[70:71], v[70:71], 0, s[8:9]
	s_waitcnt lgkmcnt(0)
	v_pk_add_f32 v[66:67], v[66:67], v[68:69]
	v_writelane_b32 v248, s5, 11
	global_store_dwordx2 v[70:71], v[66:67], off

; __device__ __forceinline__ unsigned cvt_pk_bf16(float lo, float hi) { unsigned r; asm volatile("v_cvt_pk_bf16_f32 %0, %1, %2" : "=v"(r) : "v"(lo), "v"(hi)); return r; }
; __device__ __forceinline__ f32x4 inv4_1p_exp2(f32x4 t) {
;     f32x4 d;
; #pragma unroll
;     for (int i = 0; i < 4; ++i) d[i] = 1.0f + __builtin_amdgcn_exp2f(fminf(t[i], 30.0f));
;     const float p01 = d[0] * d[1], p23 = d[2] * d[3], r = __builtin_amdgcn_rcpf(p01 * p23), r01 = r * p23, r23 = r * p01;
;     return (f32x4){r01 * d[1], r01 * d[0], r23 * d[3], r23 * d[2]};
; }
; __device__ __forceinline__ f32x4 gelu_tanh4(f32x4 x) { const f32x4 u = (x + (x * x * x) * 0.044715f) * (-2.885390081777927f * 0.7978845608028654f); return x * inv4_1p_exp2(u); }
;     __device__ __forceinline__ void operator()(const f32x4 (&acc)[2][2][4][2], const Unit& u, int wr, int wc, int fr, int fq) const {
;     ...
;             for (int m = 0; m < 4; ++m) { bf16_t* rowp = O + (size_t)(row0 + ai * HALF + m * 16) * ldc + col0;
;                 float s1 = 0.f, s2 = 0.f;
; #pragma unroll
;                 for (int bj = 0; bj < 2; ++bj) { f32x4 v0 = acc[ai][bj][m][0] + bv[bj][0], v1 = acc[ai][bj][m][1] + bv[bj][1];
;                     v0 = gelu_tanh4(v0); v1 = gelu_tanh4(v1);
;                     s1 += ((v0[0] + v0[1]) + (v0[2] + v0[3])) + ((v1[0] + v1[1]) + (v1[2] + v1[3]));
;                     s2 += ((v0[0] * v0[0] + v0[1] * v0[1]) + (v0[2] * v0[2] + v0[3] * v0[3])) + ((v1[0] * v1[0] + v1[1] * v1[1]) + (v1[2] * v1[2] + v1[3] * v1[3]));
;                     u32x4 w; w.x = cvt_pk_bf16(v0[0], v0[1]); w.y = cvt_pk_bf16(v0[2], v0[3]); w.z = cvt_pk_bf16(v1[0], v1[1]); w.w = cvt_pk_bf16(v1[2], v1[3]);
;                     *(u32x4*)(rowp + bj * HALF) = w; }
.LBB0_604:
	v_pk_add_f32 v[64:65], v[64:65], v[48:49]
	v_pk_add_f32 v[62:63], v[62:63], v[46:47]
	v_pk_add_f32 v[70:71], v[60:61], v[44:45]
	v_pk_add_f32 v[72:73], v[58:59], v[42:43]
	v_pk_mul_f32 v[58:59], v[64:65], v[64:65]
	v_pk_mul_f32 v[60:61], v[62:63], v[62:63]
	v_pk_mul_f32 v[58:59], v[64:65], v[58:59]
	v_pk_mul_f32 v[60:61], v[62:63], v[60:61]
	s_mov_b32 s2, 0x3d372713
	v_pk_fma_f32 v[58:59], v[58:59], s[2:3], v[64:65] op_sel_hi:[1,0,1]
	v_pk_fma_f32 v[60:61], v[60:61], s[2:3], v[62:63] op_sel_hi:[1,0,1]
	s_mov_b32 s4, 0xc0135761
	v_pk_mul_f32 v[58:59], v[58:59], s[4:5] op_sel_hi:[1,0]
	v_pk_mul_f32 v[60:61], v[60:61], s[4:5] op_sel_hi:[1,0]
	v_min_f32_e32 v58, 0x41f00000, v58
	v_min_f32_e32 v60, 0x41f00000, v60
	v_exp_f32_e32 v75, v60
	v_min_f32_e32 v60, 0x41f00000, v61
	v_exp_f32_e32 v61, v58
	v_min_f32_e32 v58, 0x41f00000, v59
	v_exp_f32_e32 v74, v60
	v_exp_f32_e32 v60, v58
	v_add_u32_e32 v66, 0x90, v168
	v_ashrrev_i32_e32 v67, 31, v66
	v_pk_add_f32 v[58:59], v[74:75], 1.0 op_sel_hi:[1,0]
	v_pk_add_f32 v[60:61], v[60:61], 1.0 op_sel_hi:[1,0]
	v_mul_f32_e32 v74, v59, v58
	v_mul_f32_e32 v75, v61, v60
	s_waitcnt lgkmcnt(0)
	v_lshlrev_b64 v[68:69], 12, v[66:67]
	v_mul_f32_e32 v76, v74, v75
	v_rcp_f32_e32 v77, v76
	v_lshl_add_u64 v[68:69], s[84:85], 0, v[68:69]
	v_lshl_add_u64 v[68:69], v[166:167], 1, v[68:69]
	v_pk_add_f32 v[56:57], v[56:57], v[40:41]
	v_mul_f32_e32 v76, v75, v77
	v_mul_f32_e32 v74, v74, v77
	v_pk_mul_f32 v[76:77], v[58:59], v[76:77] op_sel_hi:[1,0]
	v_pk_mul_f32 v[58:59], v[60:61], v[74:75] op_sel_hi:[1,0]
	v_pk_mul_f32 v[60:61], v[62:63], v[76:77]
	v_pk_mul_f32 v[58:59], v[64:65], v[58:59]
	v_pk_mul_f32 v[62:63], v[70:71], v[70:71]
	v_pk_mul_f32 v[64:65], v[72:73], v[72:73]
	v_pk_mul_f32 v[62:63], v[70:71], v[62:63]
	v_pk_mul_f32 v[64:65], v[72:73], v[64:65]
	v_pk_fma_f32 v[62:63], v[62:63], s[2:3], v[70:71] op_sel_hi:[1,0,1]
	v_pk_fma_f32 v[64:65], v[64:65], s[2:3], v[72:73] op_sel_hi:[1,0,1]
	v_pk_mul_f32 v[62:63], v[62:63], s[4:5] op_sel_hi:[1,0]
	v_pk_mul_f32 v[64:65], v[64:65], s[4:5] op_sel_hi:[1,0]
	v_min_f32_e32 v62, 0x41f00000, v62
	v_min_f32_e32 v64, 0x41f00000, v64
	v_exp_f32_e32 v75, v64
	v_min_f32_e32 v64, 0x41f00000, v65
	v_exp_f32_e32 v65, v62
	v_min_f32_e32 v62, 0x41f00000, v63
	v_exp_f32_e32 v74, v64
	v_exp_f32_e32 v64, v62
	v_pk_add_f32 v[54:55], v[54:55], v[38:39]
	s_and_b64 vcc, exec, s[40:41]
	v_pk_add_f32 v[62:63], v[74:75], 1.0 op_sel_hi:[1,0]
	v_pk_add_f32 v[64:65], v[64:65], 1.0 op_sel_hi:[1,0]
	v_mul_f32_e32 v74, v63, v62
	v_mul_f32_e32 v75, v65, v64
	s_nop 0
	v_mul_f32_e32 v76, v74, v75
	v_rcp_f32_e32 v77, v76
	s_nop 0
	v_mul_f32_e32 v76, v75, v77
	v_mul_f32_e32 v74, v74, v77
	v_pk_mul_f32 v[76:77], v[62:63], v[76:77] op_sel_hi:[1,0]
	v_pk_mul_f32 v[62:63], v[64:65], v[74:75] op_sel_hi:[1,0]
	v_pk_mul_f32 v[64:65], v[72:73], v[76:77]
	v_pk_mul_f32 v[62:63], v[70:71], v[62:63]
	v_cvt_pk_bf16_f32 v70, v60, v61
	v_cvt_pk_bf16_f32 v71, v58, v59
	v_cvt_pk_bf16_f32 v72, v64, v65
	s_nop 0
	v_cvt_pk_bf16_f32 v73, v62, v63
	global_store_dwordx4 v[68:69], v[70:73], off
	s_nop 1
	v_pk_add_f32 v[70:71], v[52:53], v[36:37]
	v_pk_add_f32 v[72:73], v[50:51], v[34:35]
	v_pk_mul_f32 v[50:51], v[56:57], v[56:57]
	v_pk_mul_f32 v[52:53], v[54:55], v[54:55]
	v_pk_mul_f32 v[50:51], v[56:57], v[50:51]
	v_pk_mul_f32 v[52:53], v[54:55], v[52:53]
	v_pk_fma_f32 v[50:51], v[50:51], s[2:3], v[56:57] op_sel_hi:[1,0,1]
	v_pk_fma_f32 v[52:53], v[52:53], s[2:3], v[54:55] op_sel_hi:[1,0,1]
	v_pk_mul_f32 v[50:51], v[50:51], s[4:5] op_sel_hi:[1,0]
	v_pk_mul_f32 v[52:53], v[52:53], s[4:5] op_sel_hi:[1,0]
	v_min_f32_e32 v50, 0x41f00000, v50
	v_min_f32_e32 v52, 0x41f00000, v52
	v_exp_f32_e32 v75, v52
	v_min_f32_e32 v52, 0x41f00000, v53
	v_exp_f32_e32 v53, v50
	v_min_f32_e32 v50, 0x41f00000, v51
	v_exp_f32_e32 v74, v52
	v_exp_f32_e32 v52, v50
	v_pk_add_f32 v[50:51], v[74:75], 1.0 op_sel_hi:[1,0]
	v_pk_add_f32 v[52:53], v[52:53], 1.0 op_sel_hi:[1,0]
	v_mul_f32_e32 v74, v51, v50
	v_mul_f32_e32 v75, v53, v52
	s_nop 0
	v_mul_f32_e32 v76, v74, v75
	v_rcp_f32_e32 v77, v76
	s_nop 0
	v_mul_f32_e32 v76, v75, v77
	v_mul_f32_e32 v74, v74, v77
	v_pk_mul_f32 v[76:77], v[50:51], v[76:77] op_sel_hi:[1,0]
	v_pk_mul_f32 v[50:51], v[52:53], v[74:75] op_sel_hi:[1,0]
	v_pk_mul_f32 v[52:53], v[54:55], v[76:77]
	v_pk_mul_f32 v[50:51], v[56:57], v[50:51]
	v_pk_mul_f32 v[54:55], v[70:71], v[70:71]
	v_pk_mul_f32 v[56:57], v[72:73], v[72:73]
	v_pk_mul_f32 v[54:55], v[70:71], v[54:55]
	v_pk_mul_f32 v[56:57], v[72:73], v[56:57]
	v_pk_fma_f32 v[54:55], v[54:55], s[2:3], v[70:71] op_sel_hi:[1,0,1]
	v_pk_fma_f32 v[56:57], v[56:57], s[2:3], v[72:73] op_sel_hi:[1,0,1]
	v_pk_mul_f32 v[54:55], v[54:55], s[4:5] op_sel_hi:[1,0]
	v_pk_mul_f32 v[56:57], v[56:57], s[4:5] op_sel_hi:[1,0]
	v_min_f32_e32 v54, 0x41f00000, v54
	v_min_f32_e32 v56, 0x41f00000, v56
	v_exp_f32_e32 v75, v56
	v_min_f32_e32 v56, 0x41f00000, v57
	v_exp_f32_e32 v57, v54
	v_min_f32_e32 v54, 0x41f00000, v55
	v_exp_f32_e32 v74, v56
	v_exp_f32_e32 v56, v54
	v_pk_add_f32 v[54:55], v[74:75], 1.0 op_sel_hi:[1,0]
	v_pk_add_f32 v[56:57], v[56:57], 1.0 op_sel_hi:[1,0]
	v_mul_f32_e32 v74, v55, v54
	v_mul_f32_e32 v75, v57, v56
	s_nop 0
	v_mul_f32_e32 v76, v74, v75
	v_rcp_f32_e32 v77, v76
	s_nop 0
	v_mul_f32_e32 v76, v75, v77
	v_mul_f32_e32 v74, v74, v77
	v_pk_mul_f32 v[76:77], v[54:55], v[76:77] op_sel_hi:[1,0]
	v_pk_mul_f32 v[54:55], v[56:57], v[74:75] op_sel_hi:[1,0]
	v_pk_mul_f32 v[56:57], v[72:73], v[76:77]
	v_pk_mul_f32 v[54:55], v[70:71], v[54:55]
	v_cvt_pk_bf16_f32 v70, v52, v53
	v_cvt_pk_bf16_f32 v71, v50, v51
	v_cvt_pk_bf16_f32 v72, v56, v57
	s_nop 0
	v_cvt_pk_bf16_f32 v73, v54, v55
	global_store_dwordx4 v[68:69], v[70:73], off offset:256
	s_cbranch_vccnz .LBB0_608
; __device__ __forceinline__ unsigned cvt_pk_bf16(float lo, float hi) { unsigned r; asm volatile("v_cvt_pk_bf16_f32 %0, %1, %2" : "=v"(r) : "v"(lo), "v"(hi)); return r; }
;     __device__ __forceinline__ void operator()(const f32x4 (&acc)[2][2][4][2], const Unit& u, int wr, int wc, int fr, int fq) const {
;     ...
;                     s1 += ((v0[0] + v0[1]) + (v0[2] + v0[3])) + ((v1[0] + v1[1]) + (v1[2] + v1[3]));
;                     s2 += ((v0[0] * v0[0] + v0[1] * v0[1]) + (v0[2] * v0[2] + v0[3] * v0[3])) + ((v1[0] * v1[0] + v1[1] * v1[1]) + (v1[2] * v1[2] + v1[3] * v1[3]));
;                     u32x4 w; w.x = cvt_pk_bf16(v0[0], v0[1]); w.y = cvt_pk_bf16(v0[2], v0[3]); w.z = cvt_pk_bf16(v1[0], v1[1]); w.w = cvt_pk_bf16(v1[2], v1[3]);
;                     *(u32x4*)(rowp + bj * HALF) = w; }
;                 if (u.pn * BM >= stat_col0) {
;                     s1 += __shfl_xor(s1, 16); s1 += __shfl_xor(s1, 32); s2 += __shfl_xor(s2, 16); s2 += __shfl_xor(s2, 32);
;                     if (fq == 0) { float* sp = stats + (size_t)(row0 + ai * HALF + m * 16) * 32 + (((u.pn * BM - stat_col0) >> 8) * 4 + wc) * 2; sp[0] = s1; sp[1] = s2; } } }
	v_mul_f32_e32 v75, v59, v59
	v_add_f32_e32 v86, v58, v59
	v_and_b32_e32 v59, 64, v203
	v_mul_f32_e32 v73, v58, v58
	v_mul_f32_e32 v81, v62, v62
	v_pk_mul_f32 v[92:93], v[54:55], v[54:55]
	v_pk_mul_f32 v[94:95], v[56:57], v[56:57]
	v_add_f32_e32 v90, v62, v63
	v_xor_b32_e32 v58, 16, v203
	v_add_u32_e32 v62, 64, v59
	v_mul_f32_e32 v69, v60, v60
	v_mul_f32_e32 v71, v61, v61
	v_mov_b32_e32 v96, v94
	v_mov_b32_e32 v97, v93
	v_pk_mov_b32 v[92:93], v[94:95], v[92:93] op_sel:[1,0]
	v_cmp_lt_i32_e32 vcc, v58, v62
	v_mov_b32_e32 v68, v52
	v_mov_b32_e32 v70, v53
	v_mov_b32_e32 v72, v50
	v_mov_b32_e32 v74, v51
	v_mul_f32_e32 v77, v64, v64
	v_mul_f32_e32 v79, v65, v65
	v_mul_f32_e32 v83, v63, v63
	v_mul_f32_e32 v85, v52, v52
	v_mul_f32_e32 v87, v53, v53
	v_mul_f32_e32 v89, v50, v50
	v_mul_f32_e32 v91, v51, v51
	v_pk_add_f32 v[92:93], v[92:93], v[96:97]
	v_add_f32_e32 v84, v60, v61
	v_add_f32_e32 v88, v64, v65
	v_cndmask_b32_e32 v58, v203, v58, vcc
	v_pk_add_f32 v[52:53], v[68:69], v[70:71]
	v_pk_add_f32 v[50:51], v[72:73], v[74:75]
	v_mov_b32_e32 v76, v56
	v_mov_b32_e32 v78, v57
	v_mov_b32_e32 v80, v54
	v_mov_b32_e32 v82, v55
	v_pk_add_f32 v[92:93], v[92:93], v[92:93] op_sel_hi:[0,1]
	v_lshlrev_b32_e32 v63, 2, v58
	v_pk_add_f32 v[58:59], v[84:85], v[86:87]
	v_pk_add_f32 v[60:61], v[88:89], v[90:91]
	v_pk_add_f32 v[50:51], v[52:53], v[50:51]
	v_pk_add_f32 v[52:53], v[76:77], v[78:79]
	v_pk_add_f32 v[54:55], v[80:81], v[82:83]
	v_pk_add_f32 v[58:59], v[58:59], v[60:61]
	v_mov_b32_e32 v92, v1
	v_pk_add_f32 v[52:53], v[52:53], v[54:55]
	v_pk_add_f32 v[58:59], v[58:59], v[92:93]
	v_pk_add_f32 v[50:51], v[50:51], v[52:53]
	v_xor_b32_e32 v54, 32, v203
	v_pk_add_f32 v[50:51], v[50:51], v[58:59]
	ds_bpermute_b32 v52, v63, v50
	ds_bpermute_b32 v53, v63, v51
	v_cmp_lt_i32_e32 vcc, v54, v62
	s_waitcnt lgkmcnt(0)
	v_pk_add_f32 v[50:51], v[50:51], v[52:53]
	v_cndmask_b32_e32 v54, v203, v54, vcc
	v_lshlrev_b32_e32 v54, 2, v54
	ds_bpermute_b32 v52, v54, v50
	ds_bpermute_b32 v53, v54, v51
	s_and_saveexec_b64 s[2:3], s[36:37]
	s_cbranch_execz .LBB0_607
	s_add_i32 s4, s10, 0xfffffc00
	s_lshr_b32 s4, s4, 6
	v_readlane_b32 s8, v248, 10
	v_lshlrev_b64 v[54:55], 7, v[66:67]
	s_or_b32 s4, s4, s59
	v_readlane_b32 s9, v248, 11
	v_lshl_add_u64 v[54:55], s[86:87], 0, v[54:55]
	s_lshl_b32 s8, s4, 3
	s_mov_b32 s5, s9
	v_writelane_b32 v248, s4, 10
	v_lshl_add_u64 v[54:55], v[54:55], 0, s[8:9]
	s_waitcnt lgkmcnt(0)
	v_pk_add_f32 v[50:51], v[50:51], v[52:53]
	v_writelane_b32 v248, s5, 11
	global_store_dwordx2 v[54:55], v[50:51], off

; __device__ __forceinline__ unsigned cvt_pk_bf16(float lo, float hi) { unsigned r; asm volatile("v_cvt_pk_bf16_f32 %0, %1, %2" : "=v"(r) : "v"(lo), "v"(hi)); return r; }
; __device__ __forceinline__ f32x4 inv4_1p_exp2(f32x4 t) {
;     f32x4 d;
; #pragma unroll
;     for (int i = 0; i < 4; ++i) d[i] = 1.0f + __builtin_amdgcn_exp2f(fminf(t[i], 30.0f));
;     const float p01 = d[0] * d[1], p23 = d[2] * d[3], r = __builtin_amdgcn_rcpf(p01 * p23), r01 = r * p23, r23 = r * p01;
;     return (f32x4){r01 * d[1], r01 * d[0], r23 * d[3], r23 * d[2]};
; }
; __device__ __forceinline__ f32x4 gelu_tanh4(f32x4 x) { const f32x4 u = (x + (x * x * x) * 0.044715f) * (-2.885390081777927f * 0.7978845608028654f); return x * inv4_1p_exp2(u); }
;     __device__ __forceinline__ void operator()(const f32x4 (&acc)[2][2][4][2], const Unit& u, int wr, int wc, int fr, int fq) const {
;     ...
;             for (int m = 0; m < 4; ++m) { bf16_t* rowp = O + (size_t)(row0 + ai * HALF + m * 16) * ldc + col0;
;                 float s1 = 0.f, s2 = 0.f;
; #pragma unroll
;                 for (int bj = 0; bj < 2; ++bj) { f32x4 v0 = acc[ai][bj][m][0] + bv[bj][0], v1 = acc[ai][bj][m][1] + bv[bj][1];
;                     v0 = gelu_tanh4(v0); v1 = gelu_tanh4(v1);
;                     s1 += ((v0[0] + v0[1]) + (v0[2] + v0[3])) + ((v1[0] + v1[1]) + (v1[2] + v1[3]));
;                     s2 += ((v0[0] * v0[0] + v0[1] * v0[1]) + (v0[2] * v0[2] + v0[3] * v0[3])) + ((v1[0] * v1[0] + v1[1] * v1[1]) + (v1[2] * v1[2] + v1[3] * v1[3]));
;                     u32x4 w; w.x = cvt_pk_bf16(v0[0], v0[1]); w.y = cvt_pk_bf16(v0[2], v0[3]); w.z = cvt_pk_bf16(v1[0], v1[1]); w.w = cvt_pk_bf16(v1[2], v1[3]);
;                     *(u32x4*)(rowp + bj * HALF) = w; }
.LBB0_608:
	v_pk_add_f32 v[32:33], v[32:33], v[48:49]
	v_pk_add_f32 v[30:31], v[30:31], v[46:47]
	v_pk_add_f32 v[54:55], v[28:29], v[44:45]
	v_pk_add_f32 v[56:57], v[26:27], v[42:43]
	v_pk_mul_f32 v[26:27], v[32:33], v[32:33]
	v_pk_mul_f32 v[28:29], v[30:31], v[30:31]
	v_pk_mul_f32 v[26:27], v[32:33], v[26:27]
	v_pk_mul_f32 v[28:29], v[30:31], v[28:29]
	s_mov_b32 s2, 0x3d372713
	v_pk_fma_f32 v[26:27], v[26:27], s[2:3], v[32:33] op_sel_hi:[1,0,1]
	v_pk_fma_f32 v[28:29], v[28:29], s[2:3], v[30:31] op_sel_hi:[1,0,1]
	s_mov_b32 s4, 0xc0135761
	v_pk_mul_f32 v[26:27], v[26:27], s[4:5] op_sel_hi:[1,0]
	v_pk_mul_f32 v[28:29], v[28:29], s[4:5] op_sel_hi:[1,0]
	v_min_f32_e32 v26, 0x41f00000, v26
	v_min_f32_e32 v28, 0x41f00000, v28
	v_exp_f32_e32 v59, v28
	v_min_f32_e32 v28, 0x41f00000, v29
	v_exp_f32_e32 v29, v26
	v_min_f32_e32 v26, 0x41f00000, v27
	v_exp_f32_e32 v58, v28
	v_exp_f32_e32 v28, v26
	v_add_u32_e32 v50, 0xa0, v168
	v_ashrrev_i32_e32 v51, 31, v50
	v_pk_add_f32 v[26:27], v[58:59], 1.0 op_sel_hi:[1,0]
	v_pk_add_f32 v[28:29], v[28:29], 1.0 op_sel_hi:[1,0]
	v_mul_f32_e32 v58, v27, v26
	v_mul_f32_e32 v59, v29, v28
	s_waitcnt lgkmcnt(0)
	v_lshlrev_b64 v[52:53], 12, v[50:51]
	v_mul_f32_e32 v60, v58, v59
	v_rcp_f32_e32 v61, v60
	v_lshl_add_u64 v[52:53], s[84:85], 0, v[52:53]
	v_lshl_add_u64 v[52:53], v[166:167], 1, v[52:53]
	v_pk_add_f32 v[24:25], v[24:25], v[40:41]
	v_mul_f32_e32 v60, v59, v61
	v_mul_f32_e32 v58, v58, v61
	v_pk_mul_f32 v[60:61], v[26:27], v[60:61] op_sel_hi:[1,0]
	v_pk_mul_f32 v[26:27], v[28:29], v[58:59] op_sel_hi:[1,0]
	v_pk_mul_f32 v[28:29], v[30:31], v[60:61]
	v_pk_mul_f32 v[26:27], v[32:33], v[26:27]
	v_pk_mul_f32 v[30:31], v[54:55], v[54:55]
	v_pk_mul_f32 v[32:33], v[56:57], v[56:57]
	v_pk_mul_f32 v[30:31], v[54:55], v[30:31]
	v_pk_mul_f32 v[32:33], v[56:57], v[32:33]
	v_pk_fma_f32 v[30:31], v[30:31], s[2:3], v[54:55] op_sel_hi:[1,0,1]
	v_pk_fma_f32 v[32:33], v[32:33], s[2:3], v[56:57] op_sel_hi:[1,0,1]
	v_pk_mul_f32 v[30:31], v[30:31], s[4:5] op_sel_hi:[1,0]
	v_pk_mul_f32 v[32:33], v[32:33], s[4:5] op_sel_hi:[1,0]
	v_min_f32_e32 v30, 0x41f00000, v30
	v_min_f32_e32 v32, 0x41f00000, v32
	v_exp_f32_e32 v59, v32
	v_min_f32_e32 v32, 0x41f00000, v33
	v_exp_f32_e32 v33, v30
	v_min_f32_e32 v30, 0x41f00000, v31
	v_exp_f32_e32 v58, v32
	v_exp_f32_e32 v32, v30
	v_pk_add_f32 v[22:23], v[22:23], v[38:39]
	s_and_b64 vcc, exec, s[40:41]
	v_pk_add_f32 v[30:31], v[58:59], 1.0 op_sel_hi:[1,0]
	v_pk_add_f32 v[32:33], v[32:33], 1.0 op_sel_hi:[1,0]
	v_mul_f32_e32 v58, v31, v30
	v_mul_f32_e32 v59, v33, v32
	s_nop 0
	v_mul_f32_e32 v60, v58, v59
	v_rcp_f32_e32 v61, v60
	s_nop 0
	v_mul_f32_e32 v60, v59, v61
	v_mul_f32_e32 v58, v58, v61
	v_pk_mul_f32 v[60:61], v[30:31], v[60:61] op_sel_hi:[1,0]
	v_pk_mul_f32 v[30:31], v[32:33], v[58:59] op_sel_hi:[1,0]
	v_pk_mul_f32 v[32:33], v[56:57], v[60:61]
	v_pk_mul_f32 v[30:31], v[54:55], v[30:31]
	v_cvt_pk_bf16_f32 v54, v28, v29
	v_cvt_pk_bf16_f32 v55, v26, v27
	v_cvt_pk_bf16_f32 v56, v32, v33
	s_nop 0
	v_cvt_pk_bf16_f32 v57, v30, v31
	global_store_dwordx4 v[52:53], v[54:57], off
	s_nop 1
	v_pk_add_f32 v[54:55], v[20:21], v[36:37]
	v_pk_add_f32 v[56:57], v[18:19], v[34:35]
	v_pk_mul_f32 v[18:19], v[24:25], v[24:25]
	v_pk_mul_f32 v[20:21], v[22:23], v[22:23]
	v_pk_mul_f32 v[18:19], v[24:25], v[18:19]
	v_pk_mul_f32 v[20:21], v[22:23], v[20:21]
	v_pk_fma_f32 v[18:19], v[18:19], s[2:3], v[24:25] op_sel_hi:[1,0,1]
	v_pk_fma_f32 v[20:21], v[20:21], s[2:3], v[22:23] op_sel_hi:[1,0,1]
	v_pk_mul_f32 v[18:19], v[18:19], s[4:5] op_sel_hi:[1,0]
	v_pk_mul_f32 v[20:21], v[20:21], s[4:5] op_sel_hi:[1,0]
	v_min_f32_e32 v18, 0x41f00000, v18
	v_min_f32_e32 v20, 0x41f00000, v20
	v_exp_f32_e32 v59, v20
	v_min_f32_e32 v20, 0x41f00000, v21
	v_exp_f32_e32 v21, v18
	v_min_f32_e32 v18, 0x41f00000, v19
	v_exp_f32_e32 v58, v20
	v_exp_f32_e32 v20, v18
	v_pk_add_f32 v[18:19], v[58:59], 1.0 op_sel_hi:[1,0]
	v_pk_add_f32 v[20:21], v[20:21], 1.0 op_sel_hi:[1,0]
	v_mul_f32_e32 v58, v19, v18
	v_mul_f32_e32 v59, v21, v20
	s_nop 0
	v_mul_f32_e32 v60, v58, v59
	v_rcp_f32_e32 v61, v60
	s_nop 0
	v_mul_f32_e32 v60, v59, v61
	v_mul_f32_e32 v58, v58, v61
	v_pk_mul_f32 v[60:61], v[18:19], v[60:61] op_sel_hi:[1,0]
	v_pk_mul_f32 v[18:19], v[20:21], v[58:59] op_sel_hi:[1,0]
	v_pk_mul_f32 v[20:21], v[22:23], v[60:61]
	v_pk_mul_f32 v[18:19], v[24:25], v[18:19]
	v_pk_mul_f32 v[22:23], v[54:55], v[54:55]
	v_pk_mul_f32 v[24:25], v[56:57], v[56:57]
	v_pk_mul_f32 v[22:23], v[54:55], v[22:23]
	v_pk_mul_f32 v[24:25], v[56:57], v[24:25]
	v_pk_fma_f32 v[22:23], v[22:23], s[2:3], v[54:55] op_sel_hi:[1,0,1]
	v_pk_fma_f32 v[24:25], v[24:25], s[2:3], v[56:57] op_sel_hi:[1,0,1]
	v_pk_mul_f32 v[22:23], v[22:23], s[4:5] op_sel_hi:[1,0]
	v_pk_mul_f32 v[24:25], v[24:25], s[4:5] op_sel_hi:[1,0]
	v_min_f32_e32 v22, 0x41f00000, v22
	v_min_f32_e32 v24, 0x41f00000, v24
	v_exp_f32_e32 v59, v24
	v_min_f32_e32 v24, 0x41f00000, v25
	v_exp_f32_e32 v25, v22
	v_min_f32_e32 v22, 0x41f00000, v23
	v_exp_f32_e32 v58, v24
	v_exp_f32_e32 v24, v22
	v_pk_add_f32 v[22:23], v[58:59], 1.0 op_sel_hi:[1,0]
	v_pk_add_f32 v[24:25], v[24:25], 1.0 op_sel_hi:[1,0]
	v_mul_f32_e32 v58, v23, v22
	v_mul_f32_e32 v59, v25, v24
	s_nop 0
	v_mul_f32_e32 v60, v58, v59
	v_rcp_f32_e32 v61, v60
	s_nop 0
	v_mul_f32_e32 v60, v59, v61
	v_mul_f32_e32 v58, v58, v61
	v_pk_mul_f32 v[60:61], v[22:23], v[60:61] op_sel_hi:[1,0]
	v_pk_mul_f32 v[22:23], v[24:25], v[58:59] op_sel_hi:[1,0]
	v_pk_mul_f32 v[24:25], v[56:57], v[60:61]
	v_pk_mul_f32 v[22:23], v[54:55], v[22:23]
	v_cvt_pk_bf16_f32 v54, v20, v21
	v_cvt_pk_bf16_f32 v55, v18, v19
	v_cvt_pk_bf16_f32 v56, v24, v25
	s_nop 0
	v_cvt_pk_bf16_f32 v57, v22, v23
	global_store_dwordx4 v[52:53], v[54:57], off offset:256
	s_cbranch_vccnz .LBB0_612
; __device__ __forceinline__ unsigned cvt_pk_bf16(float lo, float hi) { unsigned r; asm volatile("v_cvt_pk_bf16_f32 %0, %1, %2" : "=v"(r) : "v"(lo), "v"(hi)); return r; }
;     __device__ __forceinline__ void operator()(const f32x4 (&acc)[2][2][4][2], const Unit& u, int wr, int wc, int fr, int fq) const {
;     ...
;                     s1 += ((v0[0] + v0[1]) + (v0[2] + v0[3])) + ((v1[0] + v1[1]) + (v1[2] + v1[3]));
;                     s2 += ((v0[0] * v0[0] + v0[1] * v0[1]) + (v0[2] * v0[2] + v0[3] * v0[3])) + ((v1[0] * v1[0] + v1[1] * v1[1]) + (v1[2] * v1[2] + v1[3] * v1[3]));
;                     u32x4 w; w.x = cvt_pk_bf16(v0[0], v0[1]); w.y = cvt_pk_bf16(v0[2], v0[3]); w.z = cvt_pk_bf16(v1[0], v1[1]); w.w = cvt_pk_bf16(v1[2], v1[3]);
;                     *(u32x4*)(rowp + bj * HALF) = w; }
;                 if (u.pn * BM >= stat_col0) {
;                     s1 += __shfl_xor(s1, 16); s1 += __shfl_xor(s1, 32); s2 += __shfl_xor(s2, 16); s2 += __shfl_xor(s2, 32);
;                     if (fq == 0) { float* sp = stats + (size_t)(row0 + ai * HALF + m * 16) * 32 + (((u.pn * BM - stat_col0) >> 8) * 4 + wc) * 2; sp[0] = s1; sp[1] = s2; } } }
	v_mul_f32_e32 v59, v27, v27
	v_add_f32_e32 v70, v26, v27
	v_and_b32_e32 v27, 64, v203
	v_mul_f32_e32 v57, v26, v26
	v_mul_f32_e32 v65, v30, v30
	v_pk_mul_f32 v[76:77], v[22:23], v[22:23]
	v_pk_mul_f32 v[78:79], v[24:25], v[24:25]
	v_add_f32_e32 v74, v30, v31
	v_xor_b32_e32 v26, 16, v203
	v_add_u32_e32 v30, 64, v27
	v_mul_f32_e32 v53, v28, v28
	v_mul_f32_e32 v55, v29, v29
	v_mov_b32_e32 v80, v78
	v_mov_b32_e32 v81, v77
	v_pk_mov_b32 v[76:77], v[78:79], v[76:77] op_sel:[1,0]
	v_cmp_lt_i32_e32 vcc, v26, v30
	v_mov_b32_e32 v52, v20
	v_mov_b32_e32 v54, v21
	v_mov_b32_e32 v56, v18
	v_mov_b32_e32 v58, v19
	v_mul_f32_e32 v61, v32, v32
	v_mul_f32_e32 v63, v33, v33
	v_mul_f32_e32 v67, v31, v31
	v_mul_f32_e32 v69, v20, v20
	v_mul_f32_e32 v71, v21, v21
	v_mul_f32_e32 v73, v18, v18
	v_mul_f32_e32 v75, v19, v19
	v_pk_add_f32 v[76:77], v[76:77], v[80:81]
	v_add_f32_e32 v68, v28, v29
	v_add_f32_e32 v72, v32, v33
	v_cndmask_b32_e32 v26, v203, v26, vcc
	v_pk_add_f32 v[20:21], v[52:53], v[54:55]
	v_pk_add_f32 v[18:19], v[56:57], v[58:59]
	v_mov_b32_e32 v60, v24
	v_mov_b32_e32 v62, v25
	v_mov_b32_e32 v64, v22
	v_mov_b32_e32 v66, v23
	v_pk_add_f32 v[76:77], v[76:77], v[76:77] op_sel_hi:[0,1]
	v_lshlrev_b32_e32 v31, 2, v26
	v_pk_add_f32 v[26:27], v[68:69], v[70:71]
	v_pk_add_f32 v[28:29], v[72:73], v[74:75]
	v_pk_add_f32 v[18:19], v[20:21], v[18:19]
	v_pk_add_f32 v[20:21], v[60:61], v[62:63]
	v_pk_add_f32 v[22:23], v[64:65], v[66:67]
	v_pk_add_f32 v[26:27], v[26:27], v[28:29]
	v_mov_b32_e32 v76, v1
	v_pk_add_f32 v[20:21], v[20:21], v[22:23]
	v_pk_add_f32 v[26:27], v[26:27], v[76:77]
	v_pk_add_f32 v[18:19], v[18:19], v[20:21]
	v_xor_b32_e32 v22, 32, v203
	v_pk_add_f32 v[18:19], v[18:19], v[26:27]
	ds_bpermute_b32 v20, v31, v18
	ds_bpermute_b32 v21, v31, v19
	v_cmp_lt_i32_e32 vcc, v22, v30
	s_waitcnt lgkmcnt(0)
	v_pk_add_f32 v[18:19], v[18:19], v[20:21]
	v_cndmask_b32_e32 v22, v203, v22, vcc
	v_lshlrev_b32_e32 v22, 2, v22
	ds_bpermute_b32 v20, v22, v18
	ds_bpermute_b32 v21, v22, v19
	s_and_saveexec_b64 s[2:3], s[36:37]
	s_cbranch_execz .LBB0_611
	s_add_i32 s4, s10, 0xfffffc00
	s_lshr_b32 s4, s4, 6
	v_readlane_b32 s8, v248, 10
	v_lshlrev_b64 v[22:23], 7, v[50:51]
	s_or_b32 s4, s4, s59
	v_readlane_b32 s9, v248, 11
	v_lshl_add_u64 v[22:23], s[86:87], 0, v[22:23]
	s_lshl_b32 s8, s4, 3
	s_mov_b32 s5, s9
	v_writelane_b32 v248, s4, 10
	v_lshl_add_u64 v[22:23], v[22:23], 0, s[8:9]
	s_waitcnt lgkmcnt(0)
	v_pk_add_f32 v[18:19], v[18:19], v[20:21]
	v_writelane_b32 v248, s5, 11
	global_store_dwordx2 v[22:23], v[18:19], off

; __device__ __forceinline__ unsigned cvt_pk_bf16(float lo, float hi) { unsigned r; asm volatile("v_cvt_pk_bf16_f32 %0, %1, %2" : "=v"(r) : "v"(lo), "v"(hi)); return r; }
; __device__ __forceinline__ f32x4 inv4_1p_exp2(f32x4 t) {
;     f32x4 d;
; #pragma unroll
;     for (int i = 0; i < 4; ++i) d[i] = 1.0f + __builtin_amdgcn_exp2f(fminf(t[i], 30.0f));
;     const float p01 = d[0] * d[1], p23 = d[2] * d[3], r = __builtin_amdgcn_rcpf(p01 * p23), r01 = r * p23, r23 = r * p01;
;     return (f32x4){r01 * d[1], r01 * d[0], r23 * d[3], r23 * d[2]};
; }
; __device__ __forceinline__ f32x4 gelu_tanh4(f32x4 x) { const f32x4 u = (x + (x * x * x) * 0.044715f) * (-2.885390081777927f * 0.7978845608028654f); return x * inv4_1p_exp2(u); }
;     __device__ __forceinline__ void operator()(const f32x4 (&acc)[2][2][4][2], const Unit& u, int wr, int wc, int fr, int fq) const {
;     ...
;             for (int m = 0; m < 4; ++m) { bf16_t* rowp = O + (size_t)(row0 + ai * HALF + m * 16) * ldc + col0;
;                 float s1 = 0.f, s2 = 0.f;
; #pragma unroll
;                 for (int bj = 0; bj < 2; ++bj) { f32x4 v0 = acc[ai][bj][m][0] + bv[bj][0], v1 = acc[ai][bj][m][1] + bv[bj][1];
;                     v0 = gelu_tanh4(v0); v1 = gelu_tanh4(v1);
;                     s1 += ((v0[0] + v0[1]) + (v0[2] + v0[3])) + ((v1[0] + v1[1]) + (v1[2] + v1[3]));
;                     s2 += ((v0[0] * v0[0] + v0[1] * v0[1]) + (v0[2] * v0[2] + v0[3] * v0[3])) + ((v1[0] * v1[0] + v1[1] * v1[1]) + (v1[2] * v1[2] + v1[3] * v1[3]));
;                     u32x4 w; w.x = cvt_pk_bf16(v0[0], v0[1]); w.y = cvt_pk_bf16(v0[2], v0[3]); w.z = cvt_pk_bf16(v1[0], v1[1]); w.w = cvt_pk_bf16(v1[2], v1[3]);
;                     *(u32x4*)(rowp + bj * HALF) = w; }
.LBB0_612:
	v_pk_add_f32 v[16:17], v[16:17], v[48:49]
	v_pk_add_f32 v[14:15], v[14:15], v[46:47]
	v_pk_add_f32 v[22:23], v[12:13], v[44:45]
	v_pk_add_f32 v[24:25], v[10:11], v[42:43]
	v_pk_mul_f32 v[10:11], v[16:17], v[16:17]
	v_pk_mul_f32 v[12:13], v[14:15], v[14:15]
	v_pk_mul_f32 v[10:11], v[16:17], v[10:11]
	v_pk_mul_f32 v[12:13], v[14:15], v[12:13]
	s_mov_b32 s2, 0x3d372713
	v_pk_fma_f32 v[10:11], v[10:11], s[2:3], v[16:17] op_sel_hi:[1,0,1]
	v_pk_fma_f32 v[12:13], v[12:13], s[2:3], v[14:15] op_sel_hi:[1,0,1]
	s_mov_b32 s4, 0xc0135761
	v_pk_mul_f32 v[10:11], v[10:11], s[4:5] op_sel_hi:[1,0]
	v_pk_mul_f32 v[12:13], v[12:13], s[4:5] op_sel_hi:[1,0]
	v_min_f32_e32 v10, 0x41f00000, v10
	v_min_f32_e32 v12, 0x41f00000, v12
	v_exp_f32_e32 v27, v12
	v_min_f32_e32 v12, 0x41f00000, v13
	v_exp_f32_e32 v13, v10
	v_min_f32_e32 v10, 0x41f00000, v11
	v_exp_f32_e32 v26, v12
	v_exp_f32_e32 v12, v10
	v_add_u32_e32 v18, 0xb0, v168
	v_ashrrev_i32_e32 v19, 31, v18
	v_pk_add_f32 v[10:11], v[26:27], 1.0 op_sel_hi:[1,0]
	v_pk_add_f32 v[12:13], v[12:13], 1.0 op_sel_hi:[1,0]
	v_mul_f32_e32 v26, v11, v10
	v_mul_f32_e32 v27, v13, v12
	s_waitcnt lgkmcnt(0)
	v_lshlrev_b64 v[20:21], 12, v[18:19]
	v_mul_f32_e32 v28, v26, v27
	v_rcp_f32_e32 v29, v28
	v_lshl_add_u64 v[20:21], s[84:85], 0, v[20:21]
	v_lshl_add_u64 v[20:21], v[166:167], 1, v[20:21]
	v_pk_add_f32 v[8:9], v[8:9], v[40:41]
	v_mul_f32_e32 v28, v27, v29
	v_mul_f32_e32 v26, v26, v29
	v_pk_mul_f32 v[28:29], v[10:11], v[28:29] op_sel_hi:[1,0]
	v_pk_mul_f32 v[10:11], v[12:13], v[26:27] op_sel_hi:[1,0]
	v_pk_mul_f32 v[12:13], v[14:15], v[28:29]
	v_pk_mul_f32 v[10:11], v[16:17], v[10:11]
	v_pk_mul_f32 v[14:15], v[22:23], v[22:23]
	v_pk_mul_f32 v[16:17], v[24:25], v[24:25]
	v_pk_mul_f32 v[14:15], v[22:23], v[14:15]
	v_pk_mul_f32 v[16:17], v[24:25], v[16:17]
	v_pk_fma_f32 v[14:15], v[14:15], s[2:3], v[22:23] op_sel_hi:[1,0,1]
	v_pk_fma_f32 v[16:17], v[16:17], s[2:3], v[24:25] op_sel_hi:[1,0,1]
	v_pk_mul_f32 v[14:15], v[14:15], s[4:5] op_sel_hi:[1,0]
	v_pk_mul_f32 v[16:17], v[16:17], s[4:5] op_sel_hi:[1,0]
	v_min_f32_e32 v14, 0x41f00000, v14
	v_min_f32_e32 v16, 0x41f00000, v16
	v_exp_f32_e32 v27, v16
	v_min_f32_e32 v16, 0x41f00000, v17
	v_exp_f32_e32 v17, v14
	v_min_f32_e32 v14, 0x41f00000, v15
	v_exp_f32_e32 v26, v16
	v_exp_f32_e32 v16, v14
	v_pk_add_f32 v[6:7], v[6:7], v[38:39]
	s_and_b64 vcc, exec, s[40:41]
	v_pk_add_f32 v[14:15], v[26:27], 1.0 op_sel_hi:[1,0]
	v_pk_add_f32 v[16:17], v[16:17], 1.0 op_sel_hi:[1,0]
	v_mul_f32_e32 v26, v15, v14
	v_mul_f32_e32 v27, v17, v16
	s_nop 0
	v_mul_f32_e32 v28, v26, v27
	v_rcp_f32_e32 v29, v28
	s_nop 0
	v_mul_f32_e32 v28, v27, v29
	v_mul_f32_e32 v26, v26, v29
	v_pk_mul_f32 v[28:29], v[14:15], v[28:29] op_sel_hi:[1,0]
	v_pk_mul_f32 v[14:15], v[16:17], v[26:27] op_sel_hi:[1,0]
	v_pk_mul_f32 v[16:17], v[24:25], v[28:29]
	v_pk_mul_f32 v[14:15], v[22:23], v[14:15]
	v_cvt_pk_bf16_f32 v22, v12, v13
	v_cvt_pk_bf16_f32 v23, v10, v11
	v_cvt_pk_bf16_f32 v24, v16, v17
	s_nop 0
	v_cvt_pk_bf16_f32 v25, v14, v15
	global_store_dwordx4 v[20:21], v[22:25], off
	s_nop 1
	v_pk_add_f32 v[22:23], v[4:5], v[36:37]
	v_pk_add_f32 v[24:25], v[2:3], v[34:35]
	v_pk_mul_f32 v[2:3], v[8:9], v[8:9]
	v_pk_mul_f32 v[4:5], v[6:7], v[6:7]
	v_pk_mul_f32 v[2:3], v[8:9], v[2:3]
	v_pk_mul_f32 v[4:5], v[6:7], v[4:5]
	v_pk_fma_f32 v[2:3], v[2:3], s[2:3], v[8:9] op_sel_hi:[1,0,1]
	v_pk_fma_f32 v[4:5], v[4:5], s[2:3], v[6:7] op_sel_hi:[1,0,1]
	v_pk_mul_f32 v[2:3], v[2:3], s[4:5] op_sel_hi:[1,0]
	v_pk_mul_f32 v[4:5], v[4:5], s[4:5] op_sel_hi:[1,0]
	v_min_f32_e32 v2, 0x41f00000, v2
	v_min_f32_e32 v4, 0x41f00000, v4
	v_exp_f32_e32 v27, v4
	v_min_f32_e32 v4, 0x41f00000, v5
	v_exp_f32_e32 v5, v2
	v_min_f32_e32 v2, 0x41f00000, v3
	v_exp_f32_e32 v26, v4
	v_exp_f32_e32 v4, v2
	v_pk_add_f32 v[2:3], v[26:27], 1.0 op_sel_hi:[1,0]
	v_pk_add_f32 v[4:5], v[4:5], 1.0 op_sel_hi:[1,0]
	v_mul_f32_e32 v26, v3, v2
	v_mul_f32_e32 v27, v5, v4
	s_nop 0
	v_mul_f32_e32 v28, v26, v27
	v_rcp_f32_e32 v29, v28
	s_nop 0
	v_mul_f32_e32 v28, v27, v29
	v_mul_f32_e32 v26, v26, v29
	v_pk_mul_f32 v[28:29], v[2:3], v[28:29] op_sel_hi:[1,0]
	v_pk_mul_f32 v[2:3], v[4:5], v[26:27] op_sel_hi:[1,0]
	v_pk_mul_f32 v[4:5], v[6:7], v[28:29]
	v_pk_mul_f32 v[2:3], v[8:9], v[2:3]
	v_pk_mul_f32 v[6:7], v[22:23], v[22:23]
	v_pk_mul_f32 v[8:9], v[24:25], v[24:25]
	v_pk_mul_f32 v[6:7], v[22:23], v[6:7]
	v_pk_mul_f32 v[8:9], v[24:25], v[8:9]
	v_pk_fma_f32 v[6:7], v[6:7], s[2:3], v[22:23] op_sel_hi:[1,0,1]
	v_pk_fma_f32 v[8:9], v[8:9], s[2:3], v[24:25] op_sel_hi:[1,0,1]
	v_pk_mul_f32 v[6:7], v[6:7], s[4:5] op_sel_hi:[1,0]
	v_pk_mul_f32 v[8:9], v[8:9], s[4:5] op_sel_hi:[1,0]
	v_min_f32_e32 v6, 0x41f00000, v6
	v_min_f32_e32 v8, 0x41f00000, v8
	v_exp_f32_e32 v27, v8
	v_min_f32_e32 v8, 0x41f00000, v9
	v_exp_f32_e32 v9, v6
	v_min_f32_e32 v6, 0x41f00000, v7
	v_exp_f32_e32 v26, v8
	v_exp_f32_e32 v8, v6
	v_pk_add_f32 v[6:7], v[26:27], 1.0 op_sel_hi:[1,0]
	v_pk_add_f32 v[8:9], v[8:9], 1.0 op_sel_hi:[1,0]
	v_mul_f32_e32 v26, v7, v6
	v_mul_f32_e32 v27, v9, v8
	s_nop 0
	v_mul_f32_e32 v28, v26, v27
	v_rcp_f32_e32 v29, v28
	s_nop 0
	v_mul_f32_e32 v28, v27, v29
	v_mul_f32_e32 v26, v26, v29
	v_pk_mul_f32 v[28:29], v[6:7], v[28:29] op_sel_hi:[1,0]
	v_pk_mul_f32 v[6:7], v[8:9], v[26:27] op_sel_hi:[1,0]
	v_pk_mul_f32 v[8:9], v[24:25], v[28:29]
	v_pk_mul_f32 v[6:7], v[22:23], v[6:7]
	v_cvt_pk_bf16_f32 v22, v4, v5
	v_cvt_pk_bf16_f32 v23, v2, v3
	v_cvt_pk_bf16_f32 v24, v8, v9
	s_nop 0
	v_cvt_pk_bf16_f32 v25, v6, v7
	global_store_dwordx4 v[20:21], v[22:25], off offset:256
	s_cbranch_vccnz .LBB0_616
; __device__ __forceinline__ unsigned cvt_pk_bf16(float lo, float hi) { unsigned r; asm volatile("v_cvt_pk_bf16_f32 %0, %1, %2" : "=v"(r) : "v"(lo), "v"(hi)); return r; }
;     __device__ __forceinline__ void operator()(const f32x4 (&acc)[2][2][4][2], const Unit& u, int wr, int wc, int fr, int fq) const {
;     ...
;                     s1 += ((v0[0] + v0[1]) + (v0[2] + v0[3])) + ((v1[0] + v1[1]) + (v1[2] + v1[3]));
;                     s2 += ((v0[0] * v0[0] + v0[1] * v0[1]) + (v0[2] * v0[2] + v0[3] * v0[3])) + ((v1[0] * v1[0] + v1[1] * v1[1]) + (v1[2] * v1[2] + v1[3] * v1[3]));
;                     u32x4 w; w.x = cvt_pk_bf16(v0[0], v0[1]); w.y = cvt_pk_bf16(v0[2], v0[3]); w.z = cvt_pk_bf16(v1[0], v1[1]); w.w = cvt_pk_bf16(v1[2], v1[3]);
;                     *(u32x4*)(rowp + bj * HALF) = w; }
;                 if (u.pn * BM >= stat_col0) {
;                     s1 += __shfl_xor(s1, 16); s1 += __shfl_xor(s1, 32); s2 += __shfl_xor(s2, 16); s2 += __shfl_xor(s2, 32);
;                     if (fq == 0) { float* sp = stats + (size_t)(row0 + ai * HALF + m * 16) * 32 + (((u.pn * BM - stat_col0) >> 8) * 4 + wc) * 2; sp[0] = s1; sp[1] = s2; } } }
	v_mul_f32_e32 v27, v11, v11
	v_add_f32_e32 v38, v10, v11
	v_and_b32_e32 v11, 64, v203
	v_mul_f32_e32 v25, v10, v10
	v_mul_f32_e32 v33, v14, v14
	v_pk_mul_f32 v[44:45], v[6:7], v[6:7]
	v_pk_mul_f32 v[46:47], v[8:9], v[8:9]
	v_add_f32_e32 v42, v14, v15
	v_xor_b32_e32 v10, 16, v203
	v_add_u32_e32 v14, 64, v11
	v_mul_f32_e32 v21, v12, v12
	v_mul_f32_e32 v23, v13, v13
	v_mov_b32_e32 v48, v46
	v_mov_b32_e32 v49, v45
	v_pk_mov_b32 v[44:45], v[46:47], v[44:45] op_sel:[1,0]
	v_cmp_lt_i32_e32 vcc, v10, v14
	v_mov_b32_e32 v20, v4
	v_mov_b32_e32 v22, v5
	v_mov_b32_e32 v24, v2
	v_mov_b32_e32 v26, v3
	v_mul_f32_e32 v29, v16, v16
	v_mul_f32_e32 v31, v17, v17
	v_mul_f32_e32 v35, v15, v15
	v_mul_f32_e32 v37, v4, v4
	v_mul_f32_e32 v39, v5, v5
	v_mul_f32_e32 v41, v2, v2
	v_mul_f32_e32 v43, v3, v3
	v_pk_add_f32 v[44:45], v[44:45], v[48:49]
	v_add_f32_e32 v36, v12, v13
	v_add_f32_e32 v40, v16, v17
	v_cndmask_b32_e32 v10, v203, v10, vcc
	v_pk_add_f32 v[4:5], v[20:21], v[22:23]
	v_pk_add_f32 v[2:3], v[24:25], v[26:27]
	v_mov_b32_e32 v28, v8
	v_mov_b32_e32 v30, v9
	v_mov_b32_e32 v32, v6
	v_mov_b32_e32 v34, v7
	v_pk_add_f32 v[44:45], v[44:45], v[44:45] op_sel_hi:[0,1]
	v_lshlrev_b32_e32 v15, 2, v10
	v_pk_add_f32 v[10:11], v[36:37], v[38:39]
	v_pk_add_f32 v[12:13], v[40:41], v[42:43]
	v_pk_add_f32 v[2:3], v[4:5], v[2:3]
	v_pk_add_f32 v[4:5], v[28:29], v[30:31]
	v_pk_add_f32 v[6:7], v[32:33], v[34:35]
	v_pk_add_f32 v[10:11], v[10:11], v[12:13]
	v_mov_b32_e32 v44, v1
	v_pk_add_f32 v[4:5], v[4:5], v[6:7]
	v_pk_add_f32 v[10:11], v[10:11], v[44:45]
	v_pk_add_f32 v[2:3], v[2:3], v[4:5]
	v_xor_b32_e32 v6, 32, v203
	v_pk_add_f32 v[2:3], v[2:3], v[10:11]
	ds_bpermute_b32 v4, v15, v2
	ds_bpermute_b32 v5, v15, v3
	v_cmp_lt_i32_e32 vcc, v6, v14
	s_waitcnt lgkmcnt(0)
	v_pk_add_f32 v[2:3], v[2:3], v[4:5]
	v_cndmask_b32_e32 v6, v203, v6, vcc
	v_lshlrev_b32_e32 v6, 2, v6
	ds_bpermute_b32 v4, v6, v2
	ds_bpermute_b32 v5, v6, v3
	s_and_saveexec_b64 s[2:3], s[36:37]
	s_cbranch_execz .LBB0_615
	s_addk_i32 s10, 0xfc00
	s_lshr_b32 s4, s10, 6
	v_readlane_b32 s8, v248, 10
	v_lshlrev_b64 v[6:7], 7, v[18:19]
	s_or_b32 s4, s4, s59
	v_readlane_b32 s9, v248, 11
	v_lshl_add_u64 v[6:7], s[86:87], 0, v[6:7]
	s_lshl_b32 s8, s4, 3
	s_mov_b32 s5, s9
	v_writelane_b32 v248, s4, 10
	v_lshl_add_u64 v[6:7], v[6:7], 0, s[8:9]
	s_waitcnt lgkmcnt(0)
	v_pk_add_f32 v[2:3], v[2:3], v[4:5]
	v_writelane_b32 v248, s5, 11
	global_store_dwordx2 v[6:7], v[2:3], off

; __device__ __forceinline__ unsigned cvt_pk_bf16(float lo, float hi) { unsigned r; asm volatile("v_cvt_pk_bf16_f32 %0, %1, %2" : "=v"(r) : "v"(lo), "v"(hi)); return r; }
; __device__ __forceinline__ f32x4 inv4_1p_exp2(f32x4 t) {
;     f32x4 d;
; #pragma unroll
;     for (int i = 0; i < 4; ++i) d[i] = 1.0f + __builtin_amdgcn_exp2f(fminf(t[i], 30.0f));
;     const float p01 = d[0] * d[1], p23 = d[2] * d[3], r = __builtin_amdgcn_rcpf(p01 * p23), r01 = r * p23, r23 = r * p01;
;     return (f32x4){r01 * d[1], r01 * d[0], r23 * d[3], r23 * d[2]};
; }
; __device__ __forceinline__ f32x4 gelu_tanh4(f32x4 x) { const f32x4 u = (x + (x * x * x) * 0.044715f) * (-2.885390081777927f * 0.7978845608028654f); return x * inv4_1p_exp2(u); }
; __device__ __forceinline__ f32x4 silu4(f32x4 a) { return a * inv4_1p_exp2(a * -1.4426950408889634f); }
;     __device__ __forceinline__ void operator()(const f32x4 (&acc)[2][2][4][2], const Unit& u, int wr, int wc, int fr, int fq) const {
;         const int row0 = u.pm * BM + wr * 64 + fr; const int col0 = u.pn * HALF + wc * 32 + 8 * fq;
; #pragma unroll
;         for (int ai = 0; ai < 2; ++ai)
; #pragma unroll
;             for (int m = 0; m < 4; ++m) { bf16_t* rowp = O + (size_t)(row0 + ai * HALF + m * 16) * ldc + col0;
;                 f32x4 v0, v1;
;                 v0 = silu4(acc[ai][0][m][0]) * acc[ai][1][m][0]; v1 = silu4(acc[ai][0][m][1]) * acc[ai][1][m][1];
;                 u32x4 w; w.x = cvt_pk_bf16(v0[0], v0[1]); w.y = cvt_pk_bf16(v0[2], v0[3]); w.z = cvt_pk_bf16(v1[0], v1[1]); w.w = cvt_pk_bf16(v1[2], v1[3]);
;                 *(u32x4*)rowp = w; }
.LBB0_666:
	v_pk_mul_f32 v[164:165], v[126:127], s[94:95] op_sel_hi:[1,0]
	v_pk_mul_f32 v[162:163], v[128:129], s[94:95] op_sel_hi:[1,0]
	v_min_f32_e32 v159, 0x41f00000, v164
	v_exp_f32_e32 v167, v159
	v_min_f32_e32 v159, 0x41f00000, v165
	v_exp_f32_e32 v166, v159
	v_min_f32_e32 v159, 0x41f00000, v162
	v_exp_f32_e32 v165, v159
	v_min_f32_e32 v159, 0x41f00000, v163
	v_exp_f32_e32 v164, v159
	v_pk_add_f32 v[162:163], v[166:167], 1.0 op_sel_hi:[1,0]
	v_lshl_or_b32 v142, s33, 7, v156
	v_pk_add_f32 v[164:165], v[164:165], 1.0 op_sel_hi:[1,0]
	v_mul_f32_e32 v166, v163, v162
	v_mul_f32_e32 v167, v165, v164
	v_lshl_add_u32 v158, s34, 8, v144
	v_mul_f32_e32 v159, v166, v167
	v_rcp_f32_e32 v159, v159
	v_ashrrev_i32_e32 v143, 31, v142
	v_mov_b64_e32 v[140:141], s[84:85]
	s_movk_i32 s5, 0x1600
	v_mul_f32_e32 v168, v167, v159
	v_mul_f32_e32 v166, v166, v159
	v_pk_mul_f32 v[164:165], v[164:165], v[166:167] op_sel_hi:[1,0]
	v_pk_mul_f32 v[162:163], v[162:163], v[168:169] op_sel_hi:[1,0]
	v_pk_mul_f32 v[128:129], v[128:129], v[164:165]
	v_pk_mul_f32 v[126:127], v[126:127], v[162:163]
	v_pk_mul_f32 v[124:125], v[128:129], v[124:125]
	v_pk_mul_f32 v[122:123], v[126:127], v[122:123]
	v_pk_mul_f32 v[126:127], v[120:121], s[94:95] op_sel_hi:[1,0]
	v_pk_mul_f32 v[128:129], v[118:119], s[94:95] op_sel_hi:[1,0]
	v_min_f32_e32 v126, 0x41f00000, v126
	v_min_f32_e32 v128, 0x41f00000, v128
	v_exp_f32_e32 v163, v128
	v_min_f32_e32 v128, 0x41f00000, v129
	v_exp_f32_e32 v129, v126
	v_min_f32_e32 v126, 0x41f00000, v127
	v_exp_f32_e32 v162, v128
	v_exp_f32_e32 v128, v126
	v_mad_i64_i32 v[160:161], s[2:3], v158, s5, v[140:141]
	v_pk_add_f32 v[126:127], v[162:163], 1.0 op_sel_hi:[1,0]
	v_pk_add_f32 v[128:129], v[128:129], 1.0 op_sel_hi:[1,0]
	v_mul_f32_e32 v162, v127, v126
	v_mul_f32_e32 v163, v129, v128
	v_lshlrev_b64 v[142:143], 1, v[142:143]
	v_mul_f32_e32 v159, v162, v163
	v_rcp_f32_e32 v159, v159
	v_lshl_add_u64 v[160:161], v[160:161], 0, v[142:143]
	s_andn2_b64 vcc, exec, s[0:1]
	v_mul_f32_e32 v164, v163, v159
	v_mul_f32_e32 v162, v162, v159
	v_pk_mul_f32 v[128:129], v[128:129], v[162:163] op_sel_hi:[1,0]
	v_pk_mul_f32 v[126:127], v[126:127], v[164:165] op_sel_hi:[1,0]
	v_pk_mul_f32 v[120:121], v[120:121], v[128:129]
	v_pk_mul_f32 v[118:119], v[118:119], v[126:127]
	v_pk_mul_f32 v[120:121], v[120:121], v[116:117]
	v_pk_mul_f32 v[116:117], v[118:119], v[114:115]
	v_cvt_pk_bf16_f32 v114, v122, v123
	v_cvt_pk_bf16_f32 v115, v124, v125
	v_pk_mul_f32 v[118:119], v[110:111], s[94:95] op_sel_hi:[1,0]
	v_cvt_pk_bf16_f32 v116, v116, v117
	v_cvt_pk_bf16_f32 v117, v120, v121
	global_store_dwordx4 v[160:161], v[114:117], off
	v_min_f32_e32 v118, 0x41f00000, v118
	v_exp_f32_e32 v121, v118
	v_pk_mul_f32 v[116:117], v[112:113], s[94:95] op_sel_hi:[1,0]
	v_min_f32_e32 v118, 0x41f00000, v119
	v_min_f32_e32 v116, 0x41f00000, v116
	v_exp_f32_e32 v119, v116
	v_min_f32_e32 v116, 0x41f00000, v117
	v_exp_f32_e32 v120, v118
	v_exp_f32_e32 v118, v116
	v_or_b32_e32 v114, 16, v158
	v_mad_i64_i32 v[114:115], s[2:3], v114, s5, v[140:141]
	v_pk_add_f32 v[116:117], v[120:121], 1.0 op_sel_hi:[1,0]
	v_pk_add_f32 v[118:119], v[118:119], 1.0 op_sel_hi:[1,0]
	v_mul_f32_e32 v120, v117, v116
	v_mul_f32_e32 v121, v119, v118
	v_lshl_add_u64 v[114:115], v[114:115], 0, v[142:143]
	v_mul_f32_e32 v122, v120, v121
	v_rcp_f32_e32 v123, v122
	s_nop 0
	v_mul_f32_e32 v122, v121, v123
	v_mul_f32_e32 v120, v120, v123
	v_pk_mul_f32 v[118:119], v[118:119], v[120:121] op_sel_hi:[1,0]
	v_pk_mul_f32 v[116:117], v[116:117], v[122:123] op_sel_hi:[1,0]
	v_pk_mul_f32 v[112:113], v[112:113], v[118:119]
	v_pk_mul_f32 v[110:111], v[110:111], v[116:117]
	v_pk_mul_f32 v[108:109], v[112:113], v[108:109]
	v_pk_mul_f32 v[106:107], v[110:111], v[106:107]
	v_pk_mul_f32 v[110:111], v[104:105], s[94:95] op_sel_hi:[1,0]
	v_pk_mul_f32 v[112:113], v[102:103], s[94:95] op_sel_hi:[1,0]
	v_min_f32_e32 v110, 0x41f00000, v110
	v_min_f32_e32 v112, 0x41f00000, v112
	v_exp_f32_e32 v117, v112
	v_min_f32_e32 v112, 0x41f00000, v113
	v_exp_f32_e32 v113, v110
	v_min_f32_e32 v110, 0x41f00000, v111
	v_exp_f32_e32 v116, v112
	v_exp_f32_e32 v112, v110
	v_pk_add_f32 v[110:111], v[116:117], 1.0 op_sel_hi:[1,0]
	v_pk_add_f32 v[112:113], v[112:113], 1.0 op_sel_hi:[1,0]
	v_mul_f32_e32 v116, v111, v110
	v_mul_f32_e32 v117, v113, v112
	s_nop 0
	v_mul_f32_e32 v118, v116, v117
	v_rcp_f32_e32 v119, v118
	s_nop 0
	v_mul_f32_e32 v118, v117, v119
	v_mul_f32_e32 v116, v116, v119
	v_pk_mul_f32 v[112:113], v[112:113], v[116:117] op_sel_hi:[1,0]
	v_pk_mul_f32 v[110:111], v[110:111], v[118:119] op_sel_hi:[1,0]
	v_pk_mul_f32 v[104:105], v[104:105], v[112:113]
	v_pk_mul_f32 v[102:103], v[102:103], v[110:111]
	v_pk_mul_f32 v[104:105], v[104:105], v[100:101]
	v_pk_mul_f32 v[100:101], v[102:103], v[98:99]
	v_cvt_pk_bf16_f32 v98, v106, v107
	v_cvt_pk_bf16_f32 v99, v108, v109
	v_pk_mul_f32 v[102:103], v[94:95], s[94:95] op_sel_hi:[1,0]
	v_cvt_pk_bf16_f32 v100, v100, v101
	v_cvt_pk_bf16_f32 v101, v104, v105
	global_store_dwordx4 v[114:115], v[98:101], off
	v_min_f32_e32 v102, 0x41f00000, v102
	v_exp_f32_e32 v105, v102
	v_pk_mul_f32 v[100:101], v[96:97], s[94:95] op_sel_hi:[1,0]
	v_min_f32_e32 v102, 0x41f00000, v103
	v_min_f32_e32 v100, 0x41f00000, v100
	v_exp_f32_e32 v103, v100
	v_min_f32_e32 v100, 0x41f00000, v101
	v_exp_f32_e32 v104, v102
	v_exp_f32_e32 v102, v100
	v_or_b32_e32 v98, 32, v158
	v_mad_i64_i32 v[98:99], s[2:3], v98, s5, v[140:141]
	v_pk_add_f32 v[100:101], v[104:105], 1.0 op_sel_hi:[1,0]
	v_pk_add_f32 v[102:103], v[102:103], 1.0 op_sel_hi:[1,0]
	v_mul_f32_e32 v104, v101, v100
	v_mul_f32_e32 v105, v103, v102
	v_lshl_add_u64 v[98:99], v[98:99], 0, v[142:143]
; __device__ __forceinline__ unsigned cvt_pk_bf16(float lo, float hi) { unsigned r; asm volatile("v_cvt_pk_bf16_f32 %0, %1, %2" : "=v"(r) : "v"(lo), "v"(hi)); return r; }
; __device__ __forceinline__ f32x4 inv4_1p_exp2(f32x4 t) {
;     f32x4 d;
; #pragma unroll
;     for (int i = 0; i < 4; ++i) d[i] = 1.0f + __builtin_amdgcn_exp2f(fminf(t[i], 30.0f));
;     const float p01 = d[0] * d[1], p23 = d[2] * d[3], r = __builtin_amdgcn_rcpf(p01 * p23), r01 = r * p23, r23 = r * p01;
;     return (f32x4){r01 * d[1], r01 * d[0], r23 * d[3], r23 * d[2]};
; }
; __device__ __forceinline__ f32x4 gelu_tanh4(f32x4 x) { const f32x4 u = (x + (x * x * x) * 0.044715f) * (-2.885390081777927f * 0.7978845608028654f); return x * inv4_1p_exp2(u); }
; __device__ __forceinline__ f32x4 silu4(f32x4 a) { return a * inv4_1p_exp2(a * -1.4426950408889634f); }
;     __device__ __forceinline__ void operator()(const f32x4 (&acc)[2][2][4][2], const Unit& u, int wr, int wc, int fr, int fq) const {
;         const int row0 = u.pm * BM + wr * 64 + fr; const int col0 = u.pn * HALF + wc * 32 + 8 * fq;
; #pragma unroll
;         for (int ai = 0; ai < 2; ++ai)
; #pragma unroll
;             for (int m = 0; m < 4; ++m) { bf16_t* rowp = O + (size_t)(row0 + ai * HALF + m * 16) * ldc + col0;
;                 f32x4 v0, v1;
;                 v0 = silu4(acc[ai][0][m][0]) * acc[ai][1][m][0]; v1 = silu4(acc[ai][0][m][1]) * acc[ai][1][m][1];
;                 u32x4 w; w.x = cvt_pk_bf16(v0[0], v0[1]); w.y = cvt_pk_bf16(v0[2], v0[3]); w.z = cvt_pk_bf16(v1[0], v1[1]); w.w = cvt_pk_bf16(v1[2], v1[3]);
;                 *(u32x4*)rowp = w; }
	v_mul_f32_e32 v106, v104, v105
	v_rcp_f32_e32 v107, v106
	s_nop 0
	v_mul_f32_e32 v106, v105, v107
	v_mul_f32_e32 v104, v104, v107
	v_pk_mul_f32 v[102:103], v[102:103], v[104:105] op_sel_hi:[1,0]
	v_pk_mul_f32 v[100:101], v[100:101], v[106:107] op_sel_hi:[1,0]
	v_pk_mul_f32 v[96:97], v[96:97], v[102:103]
	v_pk_mul_f32 v[94:95], v[94:95], v[100:101]
	v_pk_mul_f32 v[92:93], v[96:97], v[92:93]
	v_pk_mul_f32 v[90:91], v[94:95], v[90:91]
	v_pk_mul_f32 v[94:95], v[88:89], s[94:95] op_sel_hi:[1,0]
	v_pk_mul_f32 v[96:97], v[86:87], s[94:95] op_sel_hi:[1,0]
	v_min_f32_e32 v94, 0x41f00000, v94
	v_min_f32_e32 v96, 0x41f00000, v96
	v_exp_f32_e32 v101, v96
	v_min_f32_e32 v96, 0x41f00000, v97
	v_exp_f32_e32 v97, v94
	v_min_f32_e32 v94, 0x41f00000, v95
	v_exp_f32_e32 v100, v96
	v_exp_f32_e32 v96, v94
	v_pk_add_f32 v[94:95], v[100:101], 1.0 op_sel_hi:[1,0]
	v_pk_add_f32 v[96:97], v[96:97], 1.0 op_sel_hi:[1,0]
	v_mul_f32_e32 v100, v95, v94
	v_mul_f32_e32 v101, v97, v96
	s_nop 0
	v_mul_f32_e32 v102, v100, v101
	v_rcp_f32_e32 v103, v102
	s_nop 0
	v_mul_f32_e32 v102, v101, v103
	v_mul_f32_e32 v100, v100, v103
	v_pk_mul_f32 v[96:97], v[96:97], v[100:101] op_sel_hi:[1,0]
	v_pk_mul_f32 v[94:95], v[94:95], v[102:103] op_sel_hi:[1,0]
	v_pk_mul_f32 v[88:89], v[88:89], v[96:97]
	v_pk_mul_f32 v[86:87], v[86:87], v[94:95]
	v_pk_mul_f32 v[88:89], v[88:89], v[84:85]
	v_pk_mul_f32 v[84:85], v[86:87], v[82:83]
	v_cvt_pk_bf16_f32 v82, v90, v91
	v_cvt_pk_bf16_f32 v83, v92, v93
	v_pk_mul_f32 v[86:87], v[78:79], s[94:95] op_sel_hi:[1,0]
	v_cvt_pk_bf16_f32 v84, v84, v85
	v_cvt_pk_bf16_f32 v85, v88, v89
	global_store_dwordx4 v[98:99], v[82:85], off
	v_min_f32_e32 v86, 0x41f00000, v86
	v_exp_f32_e32 v89, v86
	v_pk_mul_f32 v[84:85], v[80:81], s[94:95] op_sel_hi:[1,0]
	v_min_f32_e32 v86, 0x41f00000, v87
	v_min_f32_e32 v84, 0x41f00000, v84
	v_exp_f32_e32 v87, v84
	v_min_f32_e32 v84, 0x41f00000, v85
	v_exp_f32_e32 v88, v86
	v_exp_f32_e32 v86, v84
	v_or_b32_e32 v82, 48, v158
	v_mad_i64_i32 v[82:83], s[2:3], v82, s5, v[140:141]
	v_pk_add_f32 v[84:85], v[88:89], 1.0 op_sel_hi:[1,0]
	v_pk_add_f32 v[86:87], v[86:87], 1.0 op_sel_hi:[1,0]
	v_mul_f32_e32 v88, v85, v84
	v_mul_f32_e32 v89, v87, v86
	v_lshl_add_u64 v[82:83], v[82:83], 0, v[142:143]
	v_mul_f32_e32 v90, v88, v89
	v_rcp_f32_e32 v91, v90
	s_nop 0
	v_mul_f32_e32 v90, v89, v91
	v_mul_f32_e32 v88, v88, v91
	v_pk_mul_f32 v[86:87], v[86:87], v[88:89] op_sel_hi:[1,0]
	v_pk_mul_f32 v[84:85], v[84:85], v[90:91] op_sel_hi:[1,0]
	v_pk_mul_f32 v[80:81], v[80:81], v[86:87]
	v_pk_mul_f32 v[78:79], v[78:79], v[84:85]
	v_pk_mul_f32 v[76:77], v[80:81], v[76:77]
	v_pk_mul_f32 v[74:75], v[78:79], v[74:75]
	v_pk_mul_f32 v[78:79], v[72:73], s[94:95] op_sel_hi:[1,0]
	v_pk_mul_f32 v[80:81], v[70:71], s[94:95] op_sel_hi:[1,0]
	v_min_f32_e32 v78, 0x41f00000, v78
	v_min_f32_e32 v80, 0x41f00000, v80
	v_exp_f32_e32 v85, v80
	v_min_f32_e32 v80, 0x41f00000, v81
	v_exp_f32_e32 v81, v78
	v_min_f32_e32 v78, 0x41f00000, v79
	v_exp_f32_e32 v84, v80
	v_exp_f32_e32 v80, v78
	v_pk_add_f32 v[78:79], v[84:85], 1.0 op_sel_hi:[1,0]
	v_pk_add_f32 v[80:81], v[80:81], 1.0 op_sel_hi:[1,0]
	v_mul_f32_e32 v84, v79, v78
	v_mul_f32_e32 v85, v81, v80
	s_nop 0
	v_mul_f32_e32 v86, v84, v85
	v_rcp_f32_e32 v87, v86
	s_nop 0
	v_mul_f32_e32 v86, v85, v87
	v_mul_f32_e32 v84, v84, v87
	v_pk_mul_f32 v[80:81], v[80:81], v[84:85] op_sel_hi:[1,0]
	v_pk_mul_f32 v[78:79], v[78:79], v[86:87] op_sel_hi:[1,0]
	v_pk_mul_f32 v[72:73], v[72:73], v[80:81]
	v_pk_mul_f32 v[70:71], v[70:71], v[78:79]
	v_pk_mul_f32 v[72:73], v[72:73], v[68:69]
	v_pk_mul_f32 v[68:69], v[70:71], v[66:67]
	v_cvt_pk_bf16_f32 v66, v74, v75
	v_cvt_pk_bf16_f32 v67, v76, v77
	v_pk_mul_f32 v[70:71], v[62:63], s[94:95] op_sel_hi:[1,0]
	v_cvt_pk_bf16_f32 v68, v68, v69
	v_cvt_pk_bf16_f32 v69, v72, v73
	global_store_dwordx4 v[82:83], v[66:69], off
	v_min_f32_e32 v70, 0x41f00000, v70
	v_exp_f32_e32 v73, v70
	v_pk_mul_f32 v[68:69], v[64:65], s[94:95] op_sel_hi:[1,0]
	v_min_f32_e32 v70, 0x41f00000, v71
	v_min_f32_e32 v68, 0x41f00000, v68
	v_exp_f32_e32 v71, v68
	v_min_f32_e32 v68, 0x41f00000, v69
	v_exp_f32_e32 v72, v70
	v_exp_f32_e32 v70, v68
	v_add_u32_e32 v66, 0x80, v158
	v_mad_i64_i32 v[66:67], s[2:3], v66, s5, v[140:141]
	v_pk_add_f32 v[68:69], v[72:73], 1.0 op_sel_hi:[1,0]
	v_pk_add_f32 v[70:71], v[70:71], 1.0 op_sel_hi:[1,0]
	v_mul_f32_e32 v72, v69, v68
	v_mul_f32_e32 v73, v71, v70
	v_lshl_add_u64 v[66:67], v[66:67], 0, v[142:143]
	v_mul_f32_e32 v74, v72, v73
	v_rcp_f32_e32 v75, v74
	s_nop 0
	v_mul_f32_e32 v74, v73, v75
	v_mul_f32_e32 v72, v72, v75
	v_pk_mul_f32 v[70:71], v[70:71], v[72:73] op_sel_hi:[1,0]
	v_pk_mul_f32 v[68:69], v[68:69], v[74:75] op_sel_hi:[1,0]
	v_pk_mul_f32 v[64:65], v[64:65], v[70:71]
	v_pk_mul_f32 v[62:63], v[62:63], v[68:69]
	v_pk_mul_f32 v[60:61], v[64:65], v[60:61]
	v_pk_mul_f32 v[58:59], v[62:63], v[58:59]
	v_pk_mul_f32 v[62:63], v[56:57], s[94:95] op_sel_hi:[1,0]
	v_pk_mul_f32 v[64:65], v[54:55], s[94:95] op_sel_hi:[1,0]
	v_min_f32_e32 v62, 0x41f00000, v62
	v_min_f32_e32 v64, 0x41f00000, v64
	v_exp_f32_e32 v69, v64
	v_min_f32_e32 v64, 0x41f00000, v65
	v_exp_f32_e32 v65, v62
	v_min_f32_e32 v62, 0x41f00000, v63
	v_exp_f32_e32 v68, v64
	v_exp_f32_e32 v64, v62
	v_pk_add_f32 v[62:63], v[68:69], 1.0 op_sel_hi:[1,0]
	v_pk_add_f32 v[64:65], v[64:65], 1.0 op_sel_hi:[1,0]
	v_mul_f32_e32 v68, v63, v62
	v_mul_f32_e32 v69, v65, v64
	s_nop 0
	v_mul_f32_e32 v70, v68, v69
	v_rcp_f32_e32 v71, v70
	s_nop 0
	v_mul_f32_e32 v70, v69, v71
	v_mul_f32_e32 v68, v68, v71
	v_pk_mul_f32 v[64:65], v[64:65], v[68:69] op_sel_hi:[1,0]
	v_pk_mul_f32 v[62:63], v[62:63], v[70:71] op_sel_hi:[1,0]
	v_pk_mul_f32 v[56:57], v[56:57], v[64:65]
; __device__ __forceinline__ unsigned cvt_pk_bf16(float lo, float hi) { unsigned r; asm volatile("v_cvt_pk_bf16_f32 %0, %1, %2" : "=v"(r) : "v"(lo), "v"(hi)); return r; }
; #define PG8_BAR __builtin_amdgcn_s_barrier()
; __device__ __forceinline__ f32x4 inv4_1p_exp2(f32x4 t) {
;     f32x4 d;
; #pragma unroll
;     for (int i = 0; i < 4; ++i) d[i] = 1.0f + __builtin_amdgcn_exp2f(fminf(t[i], 30.0f));
;     const float p01 = d[0] * d[1], p23 = d[2] * d[3], r = __builtin_amdgcn_rcpf(p01 * p23), r01 = r * p23, r23 = r * p01;
;     return (f32x4){r01 * d[1], r01 * d[0], r23 * d[3], r23 * d[2]};
; }
; __device__ __forceinline__ f32x4 gelu_tanh4(f32x4 x) { const f32x4 u = (x + (x * x * x) * 0.044715f) * (-2.885390081777927f * 0.7978845608028654f); return x * inv4_1p_exp2(u); }
; __device__ __forceinline__ f32x4 silu4(f32x4 a) { return a * inv4_1p_exp2(a * -1.4426950408889634f); }
;     __device__ __forceinline__ void operator()(const f32x4 (&acc)[2][2][4][2], const Unit& u, int wr, int wc, int fr, int fq) const {
;         const int row0 = u.pm * BM + wr * 64 + fr; const int col0 = u.pn * HALF + wc * 32 + 8 * fq;
; #pragma unroll
;         for (int ai = 0; ai < 2; ++ai)
; #pragma unroll
;             for (int m = 0; m < 4; ++m) { bf16_t* rowp = O + (size_t)(row0 + ai * HALF + m * 16) * ldc + col0;
;                 f32x4 v0, v1;
;                 v0 = silu4(acc[ai][0][m][0]) * acc[ai][1][m][0]; v1 = silu4(acc[ai][0][m][1]) * acc[ai][1][m][1];
;                 u32x4 w; w.x = cvt_pk_bf16(v0[0], v0[1]); w.y = cvt_pk_bf16(v0[2], v0[3]); w.z = cvt_pk_bf16(v1[0], v1[1]); w.w = cvt_pk_bf16(v1[2], v1[3]);
;                 *(u32x4*)rowp = w; }
; template <class Epi, class Sched, bool ALIGN_EPI = false, bool SP2 = false>
; __device__ __forceinline__ void gemm_phase(PG8_LAS unsigned char* lds, const Gemm g, const Sched& S, const Epi& E) {
;     ...
;         if constexpr (!Epi::AFTER_DRAIN) { E(acc, cur, wr, wc, fr, fq); S.done(cur); }
;         if (!has_next) break;
; #pragma unroll
;         for (int a = 0; a < 2; ++a)
; #pragma unroll
;             for (int b = 0; b < 2; ++b)
; #pragma unroll
;                 for (int m = 0; m < 4; ++m)
; #pragma unroll
;                     for (int n = 0; n < 2; ++n) acc[a][b][m][n] = (f32x4){0.f, 0.f, 0.f, 0.f};
;         cur = nxt; cA = nA; cB = nB; ++ui;
;         if constexpr (ALIGN_EPI) { if (wr == 1) PG8_BAR; }
	v_pk_mul_f32 v[54:55], v[54:55], v[62:63]
	v_pk_mul_f32 v[56:57], v[56:57], v[52:53]
	v_pk_mul_f32 v[52:53], v[54:55], v[50:51]
	v_cvt_pk_bf16_f32 v50, v58, v59
	v_cvt_pk_bf16_f32 v51, v60, v61
	v_pk_mul_f32 v[54:55], v[46:47], s[94:95] op_sel_hi:[1,0]
	v_cvt_pk_bf16_f32 v52, v52, v53
	v_cvt_pk_bf16_f32 v53, v56, v57
	global_store_dwordx4 v[66:67], v[50:53], off
	v_min_f32_e32 v54, 0x41f00000, v54
	v_exp_f32_e32 v57, v54
	v_pk_mul_f32 v[52:53], v[48:49], s[94:95] op_sel_hi:[1,0]
	v_min_f32_e32 v54, 0x41f00000, v55
	v_min_f32_e32 v52, 0x41f00000, v52
	v_exp_f32_e32 v55, v52
	v_min_f32_e32 v52, 0x41f00000, v53
	v_exp_f32_e32 v56, v54
	v_exp_f32_e32 v54, v52
	v_add_u32_e32 v50, 0x90, v158
	v_mad_i64_i32 v[50:51], s[2:3], v50, s5, v[140:141]
	v_pk_add_f32 v[52:53], v[56:57], 1.0 op_sel_hi:[1,0]
	v_pk_add_f32 v[54:55], v[54:55], 1.0 op_sel_hi:[1,0]
	v_mul_f32_e32 v56, v53, v52
	v_mul_f32_e32 v57, v55, v54
	v_lshl_add_u64 v[50:51], v[50:51], 0, v[142:143]
	v_mul_f32_e32 v58, v56, v57
	v_rcp_f32_e32 v59, v58
	s_nop 0
	v_mul_f32_e32 v58, v57, v59
	v_mul_f32_e32 v56, v56, v59
	v_pk_mul_f32 v[54:55], v[54:55], v[56:57] op_sel_hi:[1,0]
	v_pk_mul_f32 v[52:53], v[52:53], v[58:59] op_sel_hi:[1,0]
	v_pk_mul_f32 v[48:49], v[48:49], v[54:55]
	v_pk_mul_f32 v[46:47], v[46:47], v[52:53]
	v_pk_mul_f32 v[44:45], v[48:49], v[44:45]
	v_pk_mul_f32 v[42:43], v[46:47], v[42:43]
	v_pk_mul_f32 v[46:47], v[40:41], s[94:95] op_sel_hi:[1,0]
	v_pk_mul_f32 v[48:49], v[38:39], s[94:95] op_sel_hi:[1,0]
	v_min_f32_e32 v46, 0x41f00000, v46
	v_min_f32_e32 v48, 0x41f00000, v48
	v_exp_f32_e32 v53, v48
	v_min_f32_e32 v48, 0x41f00000, v49
	v_exp_f32_e32 v49, v46
	v_min_f32_e32 v46, 0x41f00000, v47
	v_exp_f32_e32 v52, v48
	v_exp_f32_e32 v48, v46
	v_pk_add_f32 v[46:47], v[52:53], 1.0 op_sel_hi:[1,0]
	v_pk_add_f32 v[48:49], v[48:49], 1.0 op_sel_hi:[1,0]
	v_mul_f32_e32 v52, v47, v46
	v_mul_f32_e32 v53, v49, v48
	s_nop 0
	v_mul_f32_e32 v54, v52, v53
	v_rcp_f32_e32 v55, v54
	s_nop 0
	v_mul_f32_e32 v54, v53, v55
	v_mul_f32_e32 v52, v52, v55
	v_pk_mul_f32 v[48:49], v[48:49], v[52:53] op_sel_hi:[1,0]
	v_pk_mul_f32 v[46:47], v[46:47], v[54:55] op_sel_hi:[1,0]
	v_pk_mul_f32 v[40:41], v[40:41], v[48:49]
	v_pk_mul_f32 v[38:39], v[38:39], v[46:47]
	v_pk_mul_f32 v[40:41], v[40:41], v[36:37]
	v_pk_mul_f32 v[36:37], v[38:39], v[34:35]
	v_cvt_pk_bf16_f32 v34, v42, v43
	v_cvt_pk_bf16_f32 v35, v44, v45
	v_pk_mul_f32 v[38:39], v[30:31], s[94:95] op_sel_hi:[1,0]
	v_cvt_pk_bf16_f32 v36, v36, v37
	v_cvt_pk_bf16_f32 v37, v40, v41
	global_store_dwordx4 v[50:51], v[34:37], off
	v_min_f32_e32 v38, 0x41f00000, v38
	v_exp_f32_e32 v41, v38
	v_pk_mul_f32 v[36:37], v[32:33], s[94:95] op_sel_hi:[1,0]
	v_min_f32_e32 v38, 0x41f00000, v39
	v_min_f32_e32 v36, 0x41f00000, v36
	v_exp_f32_e32 v39, v36
	v_min_f32_e32 v36, 0x41f00000, v37
	v_exp_f32_e32 v40, v38
	v_exp_f32_e32 v38, v36
	v_add_u32_e32 v34, 0xa0, v158
	v_mad_i64_i32 v[34:35], s[2:3], v34, s5, v[140:141]
	v_pk_add_f32 v[36:37], v[40:41], 1.0 op_sel_hi:[1,0]
	v_pk_add_f32 v[38:39], v[38:39], 1.0 op_sel_hi:[1,0]
	v_mul_f32_e32 v40, v37, v36
	v_mul_f32_e32 v41, v39, v38
	v_lshl_add_u64 v[34:35], v[34:35], 0, v[142:143]
	v_mul_f32_e32 v42, v40, v41
	v_rcp_f32_e32 v43, v42
	s_nop 0
	v_mul_f32_e32 v42, v41, v43
	v_mul_f32_e32 v40, v40, v43
	v_pk_mul_f32 v[38:39], v[38:39], v[40:41] op_sel_hi:[1,0]
	v_pk_mul_f32 v[36:37], v[36:37], v[42:43] op_sel_hi:[1,0]
	v_pk_mul_f32 v[32:33], v[32:33], v[38:39]
	v_pk_mul_f32 v[30:31], v[30:31], v[36:37]
	v_pk_mul_f32 v[28:29], v[32:33], v[28:29]
	v_pk_mul_f32 v[26:27], v[30:31], v[26:27]
	v_pk_mul_f32 v[30:31], v[24:25], s[94:95] op_sel_hi:[1,0]
	v_pk_mul_f32 v[32:33], v[22:23], s[94:95] op_sel_hi:[1,0]
	v_min_f32_e32 v30, 0x41f00000, v30
	v_min_f32_e32 v32, 0x41f00000, v32
	v_exp_f32_e32 v37, v32
	v_min_f32_e32 v32, 0x41f00000, v33
	v_exp_f32_e32 v33, v30
	v_min_f32_e32 v30, 0x41f00000, v31
	v_exp_f32_e32 v36, v32
	v_exp_f32_e32 v32, v30
	v_pk_add_f32 v[30:31], v[36:37], 1.0 op_sel_hi:[1,0]
	v_pk_add_f32 v[32:33], v[32:33], 1.0 op_sel_hi:[1,0]
	v_mul_f32_e32 v36, v31, v30
	v_mul_f32_e32 v37, v33, v32
	s_nop 0
	v_mul_f32_e32 v38, v36, v37
	v_rcp_f32_e32 v39, v38
	s_nop 0
	v_mul_f32_e32 v38, v37, v39
	v_mul_f32_e32 v36, v36, v39
	v_pk_mul_f32 v[32:33], v[32:33], v[36:37] op_sel_hi:[1,0]
	v_pk_mul_f32 v[30:31], v[30:31], v[38:39] op_sel_hi:[1,0]
	v_pk_mul_f32 v[24:25], v[24:25], v[32:33]
	v_pk_mul_f32 v[22:23], v[22:23], v[30:31]
	v_pk_mul_f32 v[24:25], v[24:25], v[20:21]
	v_pk_mul_f32 v[20:21], v[22:23], v[18:19]
	v_cvt_pk_bf16_f32 v18, v26, v27
	v_cvt_pk_bf16_f32 v19, v28, v29
	v_pk_mul_f32 v[22:23], v[14:15], s[94:95] op_sel_hi:[1,0]
	v_cvt_pk_bf16_f32 v20, v20, v21
	v_cvt_pk_bf16_f32 v21, v24, v25
	global_store_dwordx4 v[34:35], v[18:21], off
	v_min_f32_e32 v22, 0x41f00000, v22
	v_exp_f32_e32 v25, v22
	v_pk_mul_f32 v[20:21], v[16:17], s[94:95] op_sel_hi:[1,0]
	v_min_f32_e32 v22, 0x41f00000, v23
	v_min_f32_e32 v20, 0x41f00000, v20
	v_exp_f32_e32 v23, v20
	v_min_f32_e32 v20, 0x41f00000, v21
	v_exp_f32_e32 v24, v22
	v_exp_f32_e32 v22, v20
	v_add_u32_e32 v18, 0xb0, v158
	v_mad_i64_i32 v[18:19], s[2:3], v18, s5, v[140:141]
	v_pk_add_f32 v[20:21], v[24:25], 1.0 op_sel_hi:[1,0]
	v_pk_add_f32 v[22:23], v[22:23], 1.0 op_sel_hi:[1,0]
	v_mul_f32_e32 v24, v21, v20
	v_mul_f32_e32 v25, v23, v22
	v_lshl_add_u64 v[18:19], v[18:19], 0, v[142:143]
	v_mul_f32_e32 v26, v24, v25
	v_rcp_f32_e32 v27, v26
	s_mov_b64 s[2:3], -1
	v_mul_f32_e32 v26, v25, v27
	v_mul_f32_e32 v24, v24, v27
	v_pk_mul_f32 v[22:23], v[22:23], v[24:25] op_sel_hi:[1,0]
	v_pk_mul_f32 v[20:21], v[20:21], v[26:27] op_sel_hi:[1,0]
	v_pk_mul_f32 v[16:17], v[16:17], v[22:23]
	v_pk_mul_f32 v[14:15], v[14:15], v[20:21]
	v_pk_mul_f32 v[12:13], v[16:17], v[12:13]
	v_pk_mul_f32 v[10:11], v[14:15], v[10:11]
	v_pk_mul_f32 v[14:15], v[8:9], s[94:95] op_sel_hi:[1,0]
	v_pk_mul_f32 v[16:17], v[6:7], s[94:95] op_sel_hi:[1,0]
	v_min_f32_e32 v14, 0x41f00000, v14
	v_min_f32_e32 v16, 0x41f00000, v16
	v_exp_f32_e32 v21, v16
	v_min_f32_e32 v16, 0x41f00000, v17
	v_exp_f32_e32 v17, v14
	v_min_f32_e32 v14, 0x41f00000, v15
	v_exp_f32_e32 v20, v16
	v_exp_f32_e32 v16, v14
	v_pk_add_f32 v[14:15], v[20:21], 1.0 op_sel_hi:[1,0]
	v_pk_add_f32 v[16:17], v[16:17], 1.0 op_sel_hi:[1,0]
	v_mul_f32_e32 v20, v15, v14
	v_mul_f32_e32 v21, v17, v16
	s_nop 0
	v_mul_f32_e32 v22, v20, v21
	v_rcp_f32_e32 v23, v22
	s_nop 0
	v_mul_f32_e32 v22, v21, v23
	v_mul_f32_e32 v20, v20, v23
	v_pk_mul_f32 v[16:17], v[16:17], v[20:21] op_sel_hi:[1,0]
	v_pk_mul_f32 v[14:15], v[14:15], v[22:23] op_sel_hi:[1,0]
	v_pk_mul_f32 v[8:9], v[8:9], v[16:17]
	v_pk_mul_f32 v[6:7], v[6:7], v[14:15]
	v_pk_mul_f32 v[8:9], v[8:9], v[4:5]
	v_pk_mul_f32 v[4:5], v[6:7], v[2:3]
	v_cvt_pk_bf16_f32 v2, v10, v11
	v_cvt_pk_bf16_f32 v3, v12, v13
	s_nop 0
	v_cvt_pk_bf16_f32 v4, v4, v5
	v_cvt_pk_bf16_f32 v5, v8, v9
	global_store_dwordx4 v[18:19], v[2:5], off
	s_cbranch_vccnz .LBB0_659
	s_andn2_b64 vcc, exec, s[36:37]
	s_cbranch_vccnz .LBB0_658
	s_barrier
	s_branch .LBB0_658
